# attention chunk loop: wave groups 0-3 and 4-7 staggered by one phase with ping-pong barriers (one group's softmax VALU overlaps the other's QK/PV MFMA+LDS phases); on top of v64
# speedup vs baseline: 1.0027x; 1.0027x over previous
.LBB0_247:
	v_readfirstlane_b32 s99, v182
	s_nop 3
	s_lshr_b32 s99, s99, 8
	s_ashr_i32 s0, s51, 8
	s_and_b32 s2, s51, 0xff
	s_cmp_eq_u32 s0, 1
	s_cselect_b32 s3, 4, 16
	s_cselect_b32 s4, 2, 4
	s_cmpk_lt_u32 s51, 0x100
	s_cselect_b32 s48, 0, s4
	s_cselect_b32 s9, 1, s3
	s_lshr_b32 s3, 16, s48
	s_add_i32 s3, s3, -1
	s_sub_i32 s4, 4, s48
	s_and_b32 s3, s3, s2
	s_lshr_b32 s2, s2, s4
	s_add_i32 s4, s9, -1
	s_bfe_u32 s8, s51, 0x10007
	s_and_b32 s49, s2, s4
	s_bfe_u32 s2, s51, 0x30004
	s_mul_i32 s4, s8, 0x3000000
	s_add_u32 s4, s75, s4
	v_readlane_b32 s5, v252, 33
	s_addc_u32 s5, s5, 0
	s_lshl_b32 s6, s2, 8
	v_mov_b32_e32 v36, v182
	s_add_u32 s4, s4, s6
	s_addc_u32 s5, s5, 0
	v_and_b32_e32 v34, 15, v36
	v_readfirstlane_b32 s1, v36
	v_ashrrev_i32_e32 v35, 4, v36
	s_cmp_lg_u32 s3, 0
	v_lshlrev_b32_e32 v72, 3, v34
	v_lshlrev_b32_e32 v32, 4, v34
	s_barrier
	s_cbranch_scc0 .LBB0_258
	s_lshl_b32 s52, s3, 9
	v_add_u32_e32 v26, s52, v35
	v_add_u32_e32 v0, 0xffffff80, v26
	v_mov_b32_e32 v33, v73
	v_lshlrev_b32_e32 v0, s48, v0
	v_lshl_add_u64 v[24:25], s[4:5], 0, v[32:33]
	v_add_u32_e32 v0, s49, v0
	v_add_u32_e32 v8, 0xffffffa0, v26
	v_mad_i64_i32 v[0:1], s[6:7], v0, s42, v[24:25]
	v_lshlrev_b32_e32 v8, s48, v8
	v_add_co_u32_e32 v2, vcc, 0x1000, v0
	v_add_u32_e32 v8, s49, v8
	v_subrev_u32_e32 v16, 64, v26
	v_addc_co_u32_e32 v3, vcc, 0, v1, vcc
	v_mad_i64_i32 v[8:9], s[6:7], v8, s42, v[24:25]
	v_lshlrev_b32_e32 v16, s48, v16
	v_add_co_u32_e32 v12, vcc, 0x1000, v8
	v_add_u32_e32 v16, s49, v16
	v_subrev_u32_e32 v26, 32, v26
	v_addc_co_u32_e32 v13, vcc, 0, v9, vcc
	v_mad_i64_i32 v[16:17], s[6:7], v16, s42, v[24:25]
	v_lshlrev_b32_e32 v26, s48, v26
	v_add_co_u32_e32 v20, vcc, 0x1000, v16
	v_add_u32_e32 v26, s49, v26
	s_nop 0
	v_addc_co_u32_e32 v21, vcc, 0, v17, vcc
	v_mad_i64_i32 v[24:25], s[6:7], v26, s42, v[24:25]
	v_add_co_u32_e32 v28, vcc, 0x1000, v24
	global_load_dwordx4 v[4:7], v[0:1], off offset:2048
	s_nop 0
	global_load_dwordx4 v[0:3], v[2:3], off
	v_addc_co_u32_e32 v29, vcc, 0, v25, vcc
	global_load_dwordx4 v[8:11], v[8:9], off offset:2048
	s_nop 0
	global_load_dwordx4 v[12:15], v[12:13], off
	s_nop 0
	global_load_dwordx4 v[16:19], v[16:17], off offset:2048
	s_nop 0
	global_load_dwordx4 v[20:23], v[20:21], off
	s_nop 0
	global_load_dwordx4 v[24:27], v[24:25], off offset:2048
	s_nop 0
	global_load_dwordx4 v[28:31], v[28:29], off
	s_lshl_b32 s26, s2, 7
	s_cbranch_execnz .LBB0_250

.LBB0_250:
	v_add_u32_e32 v33, s52, v35
	v_lshlrev_b32_e32 v37, s48, v33
	v_lshl_add_u64 v[74:75], v[72:73], 1, s[4:5]
	v_add_u32_e32 v37, s49, v37
	v_mad_i64_i32 v[38:39], s[6:7], v37, s42, v[74:75]
	v_add_lshl_u32 v37, v33, 32, s48
	v_add_co_u32_e32 v42, vcc, s43, v38
	v_add_u32_e32 v37, s49, v37
	s_nop 0
	v_addc_co_u32_e32 v43, vcc, 0, v39, vcc
	v_mad_i64_i32 v[46:47], s[6:7], v37, s42, v[74:75]
	v_add_lshl_u32 v37, v33, 64, s48
	v_add_co_u32_e32 v48, vcc, s43, v46
	v_add_u32_e32 v37, s49, v37
	v_add_u32_e32 v33, 0x60, v33
	global_load_dwordx4 v[38:41], v[38:39], off offset:2048
	s_nop 0
	global_load_dwordx4 v[42:45], v[42:43], off
	v_addc_co_u32_e32 v49, vcc, 0, v47, vcc
	global_load_dwordx4 v[64:67], v[46:47], off offset:2048
	global_load_dwordx4 v[68:71], v[48:49], off
	v_mad_i64_i32 v[46:47], s[6:7], v37, s42, v[74:75]
	v_lshlrev_b32_e32 v33, s48, v33
	v_add_co_u32_e32 v48, vcc, s43, v46
	v_add_u32_e32 v33, s49, v33
	s_nop 0
	v_addc_co_u32_e32 v49, vcc, 0, v47, vcc
	global_load_dwordx4 v[76:79], v[46:47], off offset:2048
	global_load_dwordx4 v[84:87], v[48:49], off
	v_mad_i64_i32 v[46:47], s[6:7], v33, s42, v[74:75]
	v_add_co_u32_e32 v48, vcc, s43, v46
	s_ashr_i32 s10, s1, 2
	s_nop 0
	v_addc_co_u32_e32 v49, vcc, 0, v47, vcc
	global_load_dwordx4 v[88:91], v[46:47], off offset:2048
	global_load_dwordx4 v[92:95], v[48:49], off
	s_movk_i32 s6, 0x110
	v_mul_lo_u32 v33, v35, s6
	s_and_b32 s27, s10, -16
	v_readlane_b32 s7, v252, 37
	v_add3_u32 v83, 0, v32, v33
	v_add3_u32 v98, s39, v32, v33
	v_add3_u32 v99, s7, v32, v33
	v_or_b32_e32 v32, s27, v34
	v_add_u32_e32 v32, s52, v32
	v_lshlrev_b32_e32 v32, s48, v32
	v_bfe_u32 v37, v36, 4, 2
	v_mov_b64_e32 v[46:47], s[4:5]
	s_add_i32 s6, s2, 1
	v_add_u32_e32 v32, s49, v32
	v_mov_b32_e32 v97, v73
	v_lshlrev_b32_e32 v96, 4, v37
	v_cvt_f32_ubyte0_e32 v100, s6
	v_mad_i64_i32 v[32:33], s[6:7], v32, s42, v[46:47]
	s_waitcnt vmcnt(15)
	ds_write_b128 v83, v[4:7]
	s_waitcnt vmcnt(14)
	ds_write_b128 v83, v[0:3] offset:34816
	s_waitcnt vmcnt(13)
	ds_write_b128 v83, v[8:11] offset:8704
	s_waitcnt vmcnt(12)
	ds_write_b128 v83, v[12:15] offset:43520
	s_waitcnt vmcnt(11)
	ds_write_b128 v83, v[16:19] offset:17408
	s_waitcnt vmcnt(10)
	ds_write_b128 v83, v[20:23] offset:52224
	s_waitcnt vmcnt(9)
	ds_write_b128 v83, v[24:27] offset:26112
	s_waitcnt vmcnt(8)
	ds_write_b128 v83, v[28:31] offset:60928
	v_lshl_add_u64 v[32:33], v[32:33], 0, v[96:97]
	global_load_dwordx4 v[48:51], v[32:33], off
	global_load_dwordx4 v[52:55], v[32:33], off offset:64
	global_load_dwordx4 v[56:59], v[32:33], off offset:128
	global_load_dwordx4 v[60:63], v[32:33], off offset:192
	s_mov_b32 s6, 0x42fc0000
	v_cmp_lt_f32_e32 vcc, s6, v100
	s_and_b64 s[6:7], vcc, exec
	s_cselect_b32 s6, 0xffffffc0, 0
	s_ashr_i32 s20, s1, 7
	s_ashr_i32 s1, s0, 31
	s_lshl_b64 s[64:65], s[0:1], 14
	s_lshl_b32 s0, s8, 13
	s_or_b32 s95, s49, s0
	s_cmp_lt_i32 s20, 4
	s_cselect_b64 s[66:67], -1, 0
	v_cndmask_b32_e32 v32, 0, v80, vcc
	v_sub_f32_e32 v32, v32, v100
	v_exp_f32_e32 v32, v32
	v_cvt_f32_ubyte0_e32 v33, s9
	v_and_b32_e32 v36, 3, v36
	v_lshlrev_b32_e32 v72, 3, v37
	v_ldexp_f32 v32, v32, s6
	v_mul_f32_e32 v32, v32, v33
	v_lshrrev_b32_e32 v33, 2, v34
	v_mul_f32_e32 v32, 0x3fb8aa3b, v32
	v_cmp_eq_u32_e64 s[0:1], 0, v37
	s_movk_i32 s24, 0x81
	s_movk_i32 s30, 0x82
	s_movk_i32 s31, 0x83
	s_movk_i32 s33, 0x84
	s_movk_i32 s34, 0x85
	s_movk_i32 s36, 0x86
	s_movk_i32 s16, 0x87
	s_waitcnt vmcnt(11)
	ds_write_b128 v98, v[38:41]
	s_waitcnt vmcnt(9)
	ds_write_b128 v98, v[64:67] offset:8704
	s_waitcnt vmcnt(7)
	ds_write_b128 v98, v[76:79] offset:17408
	ds_write_b128 v99, v[42:45]
	ds_write_b128 v99, v[68:71] offset:8704
	s_waitcnt vmcnt(6)
	ds_write_b128 v99, v[84:87] offset:17408
	s_waitcnt vmcnt(5)
	ds_write_b128 v98, v[88:91] offset:26112
	s_waitcnt vmcnt(4)
	ds_write_b128 v99, v[92:95] offset:26112
	v_lshl_add_u64 v[76:77], s[4:5], 0, v[96:97]
	s_and_b32 s4, s20, 3
	s_add_i32 s5, s20, 1
	s_cmp_lt_i32 s20, 3
	s_cselect_b64 s[68:69], -1, 0
	s_and_b32 s97, s5, 3
	s_cmp_lt_i32 s20, 2
	s_mul_i32 s96, s4, 0x2200
	s_cselect_b64 s[70:71], -1, 0
	s_xor_b32 s62, s4, 2
	s_add_i32 s4, s20, -1
	s_cmp_lt_i32 s20, 1
	s_cselect_b64 s[72:73], -1, 0
	s_and_b32 s63, s4, 3
	s_cmp_lt_i32 s20, 0
	s_cselect_b64 s[76:77], -1, 0
	s_cmp_gt_i32 s20, 3
	s_cselect_b64 s[78:79], -1, 0
	s_cmp_gt_i32 s20, 2
	s_cselect_b64 s[80:81], -1, 0
	s_cmp_gt_i32 s20, 1
	v_lshl_or_b32 v38, v33, 3, v36
	v_and_b32_e32 v40, 64, v81
	s_cselect_b64 s[82:83], -1, 0
	s_cmp_gt_i32 s20, 0
	v_mul_u32_u24_e32 v38, 0x110, v38
	v_xor_b32_e32 v39, 16, v81
	v_add_u32_e32 v40, 64, v40
	s_cselect_b64 s[84:85], -1, 0
	s_cmp_gt_i32 s20, -1
	v_add3_u32 v84, 0, v38, v96
	v_and_or_b32 v38, s10, 16, v34
	v_cmp_lt_i32_e32 vcc, v39, v40
	s_cselect_b64 s[86:87], -1, 0
	s_lshl_b32 s26, s26, 1
	v_or_b32_e32 v38, 0x80, v38
	v_cndmask_b32_e32 v39, v81, v39, vcc
	s_add_u32 s28, s56, s26
	v_sub_u32_e32 v64, v38, v72
	v_lshlrev_b32_e32 v86, 2, v39
	v_xor_b32_e32 v39, 32, v81
	s_addc_u32 s29, s57, 0
	s_lshl_b32 s2, s2, 2
	v_readlane_b32 s26, v252, 34
	v_cvt_f32_ubyte0_e32 v38, v64
	v_cmp_lt_i32_e32 vcc, v39, v40
	v_or_b32_e32 v33, v72, v33
	s_add_u32 s88, s26, s2
	v_readlane_b32 s2, v252, 35
	v_mul_f32_e64 v85, -v32, v38
	v_cndmask_b32_e32 v39, v81, v39, vcc
	v_mul_u32_u24_e32 v33, 0x110, v33
	v_lshlrev_b32_e32 v36, 3, v36
	s_addc_u32 s89, s2, 0
	s_add_i32 s2, s52, s27
	v_lshlrev_b32_e32 v87, 2, v39
	v_add3_u32 v88, v36, s94, v33
	v_fma_f32 v89, 0, v32, v85
	v_fma_f32 v90, -v32, v38, v32
	v_fma_f32 v91, 2.0, v32, v85
	v_fmamk_f32 v92, v32, 0x40400000, v85
	v_fma_f32 v93, 4.0, v32, v85
	v_fmamk_f32 v94, v32, 0x40a00000, v85
	v_fmamk_f32 v95, v32, 0x40c00000, v85
	v_fmamk_f32 v96, v32, 0x40e00000, v85
	s_movk_i32 s18, 0x88
	v_fmamk_f32 v97, v32, 0x42000000, v85
	v_fmamk_f32 v98, v32, 0x42040000, v85
	v_fmamk_f32 v99, v32, 0x42080000, v85
	v_fmamk_f32 v100, v32, 0x420c0000, v85
	v_fmamk_f32 v101, v32, 0x42100000, v85
	v_fmamk_f32 v102, v32, 0x42140000, v85
	v_fmamk_f32 v103, v32, 0x42180000, v85
	v_fmamk_f32 v104, v32, 0x421c0000, v85
	v_fmamk_f32 v105, v32, 0x42800000, v85
	v_fmamk_f32 v106, v32, 0x42820000, v85
	v_fmamk_f32 v107, v32, 0x42840000, v85
	v_fmamk_f32 v108, v32, 0x42860000, v85
	v_fmamk_f32 v109, v32, 0x42880000, v85
	v_fmamk_f32 v110, v32, 0x428a0000, v85
	v_fmamk_f32 v111, v32, 0x428c0000, v85
	v_fmamk_f32 v112, v32, 0x428e0000, v85
	v_fmamk_f32 v113, v32, 0x42c00000, v85
	v_fmamk_f32 v114, v32, 0x42c20000, v85
	v_fmamk_f32 v115, v32, 0x42c40000, v85
	v_fmamk_f32 v116, v32, 0x42c60000, v85
	v_fmamk_f32 v117, v32, 0x42c80000, v85
	v_fmamk_f32 v118, v32, 0x42ca0000, v85
	v_fmamk_f32 v119, v32, 0x42cc0000, v85
	v_fmamk_f32 v120, v32, 0x42ce0000, v85
	v_fmamk_f32 v121, v32, 0x43000000, v85
	s_movk_i32 s20, 0x7f
	v_fmamk_f32 v122, v32, 0x43010000, v85
	s_movk_i32 s22, 0x80
	v_fmamk_f32 v123, v32, 0x43020000, v85
	v_fmamk_f32 v124, v32, 0x43030000, v85
	v_lshl_add_u64 v[78:79], s[28:29], 0, v[72:73]
	v_add_u32_e32 v72, s2, v34
	v_fmamk_f32 v125, v32, 0x43040000, v85
	v_fmamk_f32 v126, v32, 0x43050000, v85
	v_fmamk_f32 v127, v32, 0x43060000, v85
	v_fmac_f32_e32 v85, 0x43070000, v32
	v_add_u32_e32 v128, s52, v35
	s_waitcnt vmcnt(3)
	v_mov_b64_e32 v[32:33], v[48:49]
	s_waitcnt vmcnt(2)
	v_mov_b64_e32 v[36:37], v[52:53]
	s_waitcnt vmcnt(1)
	v_mov_b64_e32 v[40:41], v[56:57]
	s_waitcnt vmcnt(0)
	v_mov_b64_e32 v[44:45], v[60:61]
	s_mov_b32 s53, 1
	s_mov_b32 s3, 0
	s_mulk_i32 s97, 0x2200
	s_mulk_i32 s62, 0x2200
	s_mulk_i32 s63, 0x2200
	v_cmp_gt_u32_e64 s[4:5], s24, v64
	v_cmp_gt_u32_e64 s[6:7], s30, v64
	v_cmp_gt_u32_e64 s[8:9], s31, v64
	v_cmp_gt_u32_e64 s[10:11], s33, v64
	v_cmp_gt_u32_e64 s[12:13], s34, v64
	v_cmp_gt_u32_e64 s[14:15], s36, v64
	v_cmp_gt_u32_e64 s[16:17], s16, v64
	v_cmp_gt_u32_e64 s[18:19], s18, v64
	v_cmp_lt_u32_e64 s[20:21], s20, v64
	v_cmp_lt_u32_e64 s[22:23], s22, v64
	v_cmp_lt_u32_e64 s[24:25], s24, v64
	v_cmp_lt_u32_e64 s[26:27], s30, v64
	v_mov_b64_e32 v[34:35], v[50:51]
	v_mov_b64_e32 v[38:39], v[54:55]
	v_mov_b64_e32 v[42:43], v[58:59]
	v_mov_b64_e32 v[46:47], v[62:63]
	v_cmp_lt_u32_e64 s[28:29], s31, v64
	v_cmp_lt_u32_e64 s[30:31], s33, v64
	v_cmp_lt_u32_e64 s[34:35], s34, v64
	v_cmp_lt_u32_e64 s[36:37], s36, v64
	s_waitcnt lgkmcnt(0)
	s_barrier
	s_branch .LBB0_252
	s_nop 0
	s_nop 0
	s_nop 0
	s_nop 0
	s_nop 0
	s_nop 0
	s_nop 0
	s_nop 0
	s_nop 0
	s_nop 0
	s_nop 0
	s_nop 0
	s_nop 0
	s_nop 0
	s_nop 0
	s_nop 0
	s_nop 0
	s_nop 0
	s_nop 0
	s_nop 0
	s_nop 0
	s_nop 0
	s_nop 0
	s_nop 0
	s_nop 0
	s_nop 0
	s_nop 0
	s_nop 0
	s_nop 0
	s_nop 0
	s_nop 0
	s_nop 0
	s_nop 0
	s_nop 0
	s_nop 0
	s_nop 0
	s_nop 0
	s_nop 0
	s_nop 0
	s_nop 0
	s_nop 0
	s_nop 0
	s_nop 0
	s_nop 0
	s_nop 0
	s_nop 0
	s_nop 0
	s_nop 0
	s_nop 0
	s_nop 0
	s_nop 0
	s_nop 0
	s_nop 0
	s_nop 0
	s_nop 0
	s_nop 0
	s_nop 0
	s_nop 0
	s_nop 0
	s_nop 0
	s_nop 0

.LBB0_254:
	s_cmp_eq_u32 s99, 0
	s_cbranch_scc1 .Lstg_p0_a
	s_barrier
.Lstg_p0_a:
	s_add_i32 s2, s53, -1
	s_add_i32 s60, s52, s3
	s_and_b32 s50, s2, 1
	s_and_b32 s61, s53, 1
	s_and_b64 s[40:41], s[66:67], exec
	s_cselect_b32 s2, s50, s61
	s_mul_i32 s38, s2, 0x11000
	s_add_i32 s38, s38, s96
	s_and_b64 s[40:41], s[68:69], exec
	s_cselect_b32 s2, s50, s61
	s_mul_i32 s33, s2, 0x11000
	s_add_i32 s33, s33, s97
	v_add_u32_e32 v146, s38, v84
	v_lshlrev_b32_e32 v129, s48, v64
	s_and_b64 s[40:41], s[70:71], exec
	ds_read_b128 v[64:67], v146
	ds_read_b128 v[68:71], v146 offset:64
	ds_read_b128 v[130:133], v146 offset:128
	ds_read_b128 v[134:137], v146 offset:192
	ds_read_b128 v[138:141], v146 offset:1088
	ds_read_b128 v[142:145], v146 offset:1152
	ds_read_b128 v[148:151], v146 offset:1216
	ds_read_b128 v[152:155], v146 offset:1280
	v_add_u32_e32 v146, s33, v84
	s_cselect_b32 s2, s50, s61
	ds_read_b128 v[156:159], v146
	ds_read_b128 v[160:163], v146 offset:64
	ds_read_b128 v[164:167], v146 offset:128
	ds_read_b128 v[168:171], v146 offset:192
	ds_read_b128 v[172:175], v146 offset:1088
	ds_read_b128 v[176:179], v146 offset:1152
	ds_read_b128 v[184:187], v146 offset:1216
	ds_read_b128 v[188:191], v146 offset:1280
	s_mul_i32 s2, s2, 0x11000
	s_add_i32 s2, s2, s62
	s_and_b64 s[40:41], s[72:73], exec
	s_cselect_b32 s40, s50, s61
	s_mul_i32 s41, s40, 0x11000
	s_add_i32 s41, s41, s63
	s_and_b64 vcc, s[76:77], exec
	s_cselect_b32 s40, s50, s61
	s_mul_i32 s40, s40, 0x11000
	s_add_i32 s40, s40, s96
	s_waitcnt lgkmcnt(14)
	v_mfma_f32_16x16x32_bf16 v[64:67], v[64:67], v[48:51], 0
	v_mfma_f32_16x16x32_bf16 v[64:67], v[68:71], v[52:55], v[64:67]
	s_waitcnt lgkmcnt(11)
	v_mfma_f32_16x16x32_bf16 v[68:71], v[138:141], v[48:51], 0
	s_waitcnt lgkmcnt(10)
	v_mfma_f32_16x16x32_bf16 v[68:71], v[142:145], v[52:55], v[68:71]
	v_mfma_f32_16x16x32_bf16 v[64:67], v[130:133], v[56:59], v[64:67]
	s_waitcnt lgkmcnt(9)
	v_mfma_f32_16x16x32_bf16 v[68:71], v[148:151], v[56:59], v[68:71]
	v_mfma_f32_16x16x32_bf16 v[64:67], v[134:137], v[60:63], v[64:67]
	s_waitcnt lgkmcnt(8)
	v_mfma_f32_16x16x32_bf16 v[68:71], v[152:155], v[60:63], v[68:71]
	v_add_u32_e32 v146, s2, v84
	ds_read_b128 v[130:133], v146
	ds_read_b128 v[134:137], v146 offset:64
	ds_read_b128 v[138:141], v146 offset:128
	ds_read_b128 v[142:145], v146 offset:192
	ds_read_b128 v[148:151], v146 offset:1088
	ds_read_b128 v[152:155], v146 offset:1152
	ds_read_b128 v[192:195], v146 offset:1216
	ds_read_b128 v[196:199], v146 offset:1280
	s_waitcnt lgkmcnt(14)
	v_mfma_f32_16x16x32_bf16 v[156:159], v[156:159], v[48:51], 0
	v_mfma_f32_16x16x32_bf16 v[156:159], v[160:163], v[52:55], v[156:159]
	s_waitcnt lgkmcnt(11)
	v_mfma_f32_16x16x32_bf16 v[160:163], v[172:175], v[48:51], 0
	s_waitcnt lgkmcnt(10)
	v_mfma_f32_16x16x32_bf16 v[160:163], v[176:179], v[52:55], v[160:163]
	v_mfma_f32_16x16x32_bf16 v[156:159], v[164:167], v[56:59], v[156:159]
	s_waitcnt lgkmcnt(9)
	v_mfma_f32_16x16x32_bf16 v[160:163], v[184:187], v[56:59], v[160:163]
	v_mfma_f32_16x16x32_bf16 v[156:159], v[168:171], v[60:63], v[156:159]
	s_waitcnt lgkmcnt(8)
	v_mfma_f32_16x16x32_bf16 v[160:163], v[188:191], v[60:63], v[160:163]
	v_add_u32_e32 v146, s41, v84
	ds_read_b128 v[164:167], v146
	ds_read_b128 v[168:171], v146 offset:64
	ds_read_b128 v[172:175], v146 offset:128
	ds_read_b128 v[176:179], v146 offset:192
	ds_read_b128 v[184:187], v146 offset:1088
	ds_read_b128 v[188:191], v146 offset:1152
	ds_read_b128 v[200:203], v146 offset:1216
	ds_read_b128 v[204:207], v146 offset:1280
	s_waitcnt lgkmcnt(14)
	v_mfma_f32_16x16x32_bf16 v[130:133], v[130:133], v[48:51], 0
	v_mfma_f32_16x16x32_bf16 v[130:133], v[134:137], v[52:55], v[130:133]
	s_waitcnt lgkmcnt(11)
	v_mfma_f32_16x16x32_bf16 v[134:137], v[148:151], v[48:51], 0
	v_mfma_f32_16x16x32_bf16 v[130:133], v[138:141], v[56:59], v[130:133]
	s_waitcnt lgkmcnt(10)
	v_mfma_f32_16x16x32_bf16 v[134:137], v[152:155], v[52:55], v[134:137]
	v_mfma_f32_16x16x32_bf16 v[130:133], v[142:145], v[60:63], v[130:133]
	s_waitcnt lgkmcnt(9)
	v_mfma_f32_16x16x32_bf16 v[134:137], v[192:195], v[56:59], v[134:137]
	s_waitcnt lgkmcnt(8)
	v_mfma_f32_16x16x32_bf16 v[134:137], v[196:199], v[60:63], v[134:137]
	v_add_u32_e32 v146, s40, v84
	ds_read_b128 v[138:141], v146
	ds_read_b128 v[142:145], v146 offset:64
	ds_read_b128 v[148:151], v146 offset:128
	ds_read_b128 v[152:155], v146 offset:192
	ds_read_b128 v[192:195], v146 offset:1088
	ds_read_b128 v[196:199], v146 offset:1152
	ds_read_b128 v[208:211], v146 offset:1216
	ds_read_b128 v[212:215], v146 offset:1280
	s_waitcnt lgkmcnt(14)
	v_mfma_f32_16x16x32_bf16 v[164:167], v[164:167], v[48:51], 0
	v_mfma_f32_16x16x32_bf16 v[164:167], v[168:171], v[52:55], v[164:167]
	s_waitcnt lgkmcnt(11)
	v_mfma_f32_16x16x32_bf16 v[168:171], v[184:187], v[48:51], 0
	s_waitcnt lgkmcnt(10)
	v_mfma_f32_16x16x32_bf16 v[168:171], v[188:191], v[52:55], v[168:171]
	v_mfma_f32_16x16x32_bf16 v[164:167], v[172:175], v[56:59], v[164:167]
	s_waitcnt lgkmcnt(9)
	v_mfma_f32_16x16x32_bf16 v[168:171], v[200:203], v[56:59], v[168:171]
	v_mfma_f32_16x16x32_bf16 v[164:167], v[176:179], v[60:63], v[164:167]
	s_waitcnt lgkmcnt(8)
	v_mfma_f32_16x16x32_bf16 v[168:171], v[204:207], v[60:63], v[168:171]
	s_waitcnt lgkmcnt(7)
	v_mfma_f32_16x16x32_bf16 v[138:141], v[138:141], v[48:51], 0
	s_waitcnt lgkmcnt(3)
	v_mfma_f32_16x16x32_bf16 v[48:51], v[192:195], v[48:51], 0
	s_waitcnt lgkmcnt(2)
	v_mfma_f32_16x16x32_bf16 v[48:51], v[196:199], v[52:55], v[48:51]
	v_mfma_f32_16x16x32_bf16 v[138:141], v[142:145], v[52:55], v[138:141]
	s_waitcnt lgkmcnt(1)
	v_mfma_f32_16x16x32_bf16 v[48:51], v[208:211], v[56:59], v[48:51]
	v_mfma_f32_16x16x32_bf16 v[138:141], v[148:151], v[56:59], v[138:141]
	s_waitcnt lgkmcnt(0)
	v_mfma_f32_16x16x32_bf16 v[48:51], v[212:215], v[60:63], v[48:51]
	v_mfma_f32_16x16x32_bf16 v[138:141], v[152:155], v[60:63], v[138:141]
	s_barrier
	s_cmp_lg_u32 s60, 0
	s_cselect_b64 s[92:93], -1, 0
	s_or_b64 s[60:61], s[92:93], s[78:79]
	v_fmamk_f32 v52, v64, 0x3e0293ee, v89
	s_and_b64 vcc, s[60:61], s[4:5]
	v_cndmask_b32_e32 v52, v82, v52, vcc
	v_fmamk_f32 v53, v65, 0x3e0293ee, v90
	s_and_b64 vcc, s[60:61], s[6:7]
	v_cndmask_b32_e32 v53, v82, v53, vcc
	v_fmamk_f32 v55, v66, 0x3e0293ee, v91
	s_and_b64 vcc, s[60:61], s[8:9]
	v_cndmask_b32_e32 v55, v82, v55, vcc
	v_fmamk_f32 v56, v67, 0x3e0293ee, v92
	s_and_b64 vcc, s[60:61], s[10:11]
	v_cndmask_b32_e32 v56, v82, v56, vcc
	v_fmamk_f32 v57, v68, 0x3e0293ee, v93
	s_and_b64 vcc, s[60:61], s[12:13]
	v_cndmask_b32_e32 v57, v82, v57, vcc
	v_fmamk_f32 v58, v69, 0x3e0293ee, v94
	s_and_b64 vcc, s[60:61], s[14:15]
	v_cndmask_b32_e32 v58, v82, v58, vcc
	v_fmamk_f32 v59, v70, 0x3e0293ee, v95
	s_and_b64 vcc, s[60:61], s[16:17]
	v_cndmask_b32_e32 v59, v82, v59, vcc
	v_fmamk_f32 v60, v71, 0x3e0293ee, v96
	s_and_b64 vcc, s[60:61], s[18:19]
	v_cndmask_b32_e32 v60, v82, v60, vcc
	v_fmamk_f32 v61, v156, 0x3e0293ee, v97
	s_or_b64 vcc, s[92:93], s[80:81]
	v_fmamk_f32 v62, v157, 0x3e0293ee, v98
	v_fmamk_f32 v63, v158, 0x3e0293ee, v99
	v_fmamk_f32 v64, v159, 0x3e0293ee, v100
	v_fmamk_f32 v65, v160, 0x3e0293ee, v101
	v_fmamk_f32 v66, v161, 0x3e0293ee, v102
	v_fmamk_f32 v67, v162, 0x3e0293ee, v103
	v_fmamk_f32 v68, v163, 0x3e0293ee, v104
	v_cndmask_b32_e32 v61, v82, v61, vcc
	v_cndmask_b32_e32 v62, v82, v62, vcc
	v_cndmask_b32_e32 v63, v82, v63, vcc
	v_cndmask_b32_e32 v64, v82, v64, vcc
	v_cndmask_b32_e32 v65, v82, v65, vcc
	v_cndmask_b32_e32 v66, v82, v66, vcc
	v_cndmask_b32_e32 v67, v82, v67, vcc
	v_cndmask_b32_e32 v68, v82, v68, vcc
	v_fmamk_f32 v69, v130, 0x3e0293ee, v105
	s_or_b64 vcc, s[92:93], s[82:83]
	v_fmamk_f32 v130, v133, 0x3e0293ee, v108
	v_fmamk_f32 v70, v131, 0x3e0293ee, v106
	v_cndmask_b32_e32 v131, v82, v130, vcc
	v_fmamk_f32 v130, v134, 0x3e0293ee, v109
	v_fmamk_f32 v71, v132, 0x3e0293ee, v107
	v_cndmask_b32_e32 v132, v82, v130, vcc
	v_fmamk_f32 v130, v135, 0x3e0293ee, v110
	v_max3_f32 v54, v52, s74, v53
	v_cndmask_b32_e32 v133, v82, v130, vcc
	v_fmamk_f32 v130, v136, 0x3e0293ee, v111
	v_max3_f32 v54, v54, v55, v56
	v_cndmask_b32_e32 v134, v82, v130, vcc
	v_fmamk_f32 v130, v137, 0x3e0293ee, v112
	v_max3_f32 v54, v54, v57, v58
	v_cndmask_b32_e32 v69, v82, v69, vcc
	v_cndmask_b32_e32 v70, v82, v70, vcc
	v_cndmask_b32_e32 v71, v82, v71, vcc
	v_cndmask_b32_e32 v135, v82, v130, vcc
	v_fmamk_f32 v130, v164, 0x3e0293ee, v113
	s_or_b64 vcc, s[92:93], s[84:85]
	v_max3_f32 v54, v54, v59, v60
	v_cndmask_b32_e32 v136, v82, v130, vcc
	v_fmamk_f32 v130, v165, 0x3e0293ee, v114
	v_max3_f32 v54, v54, v61, v62
	v_cndmask_b32_e32 v137, v82, v130, vcc
	v_fmamk_f32 v130, v166, 0x3e0293ee, v115
	v_max3_f32 v54, v54, v63, v64
	v_cndmask_b32_e32 v142, v82, v130, vcc
	v_fmamk_f32 v130, v167, 0x3e0293ee, v116
	v_max3_f32 v54, v54, v65, v66
	v_cndmask_b32_e32 v143, v82, v130, vcc
	v_fmamk_f32 v130, v168, 0x3e0293ee, v117
	v_max3_f32 v54, v54, v67, v68
	v_cndmask_b32_e32 v144, v82, v130, vcc
	v_fmamk_f32 v130, v169, 0x3e0293ee, v118
	v_max3_f32 v54, v54, v69, v70
	v_cndmask_b32_e32 v145, v82, v130, vcc
	v_fmamk_f32 v130, v170, 0x3e0293ee, v119
	v_max3_f32 v54, v54, v71, v131
	v_cndmask_b32_e32 v146, v82, v130, vcc
	v_fmamk_f32 v130, v171, 0x3e0293ee, v120
	s_or_b64 s[60:61], s[92:93], s[86:87]
	v_max3_f32 v54, v54, v132, v133
	v_cndmask_b32_e32 v147, v82, v130, vcc
	v_fmamk_f32 v130, v138, 0x3e0293ee, v121
	s_and_b64 vcc, s[60:61], s[20:21]
	v_max3_f32 v54, v54, v134, v135
	v_cndmask_b32_e32 v138, v82, v130, vcc
	v_fmamk_f32 v130, v139, 0x3e0293ee, v122
	s_and_b64 vcc, s[60:61], s[22:23]
	v_max3_f32 v54, v54, v136, v137
	v_cndmask_b32_e32 v139, v82, v130, vcc
	v_fmamk_f32 v130, v140, 0x3e0293ee, v123
	s_and_b64 vcc, s[60:61], s[24:25]
	v_max3_f32 v54, v54, v142, v143
	v_cndmask_b32_e32 v140, v82, v130, vcc
	v_fmamk_f32 v130, v141, 0x3e0293ee, v124
	s_and_b64 vcc, s[60:61], s[26:27]
	v_max3_f32 v54, v54, v144, v145
	v_cndmask_b32_e32 v141, v82, v130, vcc
	v_fmamk_f32 v48, v48, 0x3e0293ee, v125
	s_and_b64 vcc, s[60:61], s[28:29]
	v_max3_f32 v54, v54, v146, v147
	v_cndmask_b32_e32 v48, v82, v48, vcc
	v_fmamk_f32 v49, v49, 0x3e0293ee, v126
	s_and_b64 vcc, s[60:61], s[30:31]
	v_max3_f32 v54, v54, v138, v139
	v_cndmask_b32_e32 v49, v82, v49, vcc
	v_fmamk_f32 v50, v50, 0x3e0293ee, v127
	s_and_b64 vcc, s[60:61], s[34:35]
	v_max3_f32 v54, v54, v140, v141
	v_cndmask_b32_e32 v50, v82, v50, vcc
	v_fmamk_f32 v51, v51, 0x3e0293ee, v85
	s_and_b64 vcc, s[60:61], s[36:37]
	v_max3_f32 v54, v54, v48, v49
	v_cndmask_b32_e32 v51, v82, v51, vcc
	v_max3_f32 v54, v54, v50, v51
	v_mov_b32_e32 v130, v54
	s_nop 1
	v_permlane16_swap_b32 v54, v130
	s_waitcnt lgkmcnt(0)
	v_max_f32_e32 v130, v130, v130
	v_max_f32_e32 v54, v54, v130
	v_mov_b32_e32 v130, v54
	s_nop 1
	v_permlane32_swap_b32 v54, v130
	s_waitcnt lgkmcnt(0)
	v_max_f32_e32 v130, v130, v130
	v_max_f32_e32 v130, v54, v130
	v_sub_f32_e32 v52, v52, v130
	v_exp_f32_e32 v52, v52
	v_sub_f32_e32 v53, v53, v130
	v_exp_f32_e32 v53, v53
	v_sub_f32_e32 v54, v55, v130
	v_exp_f32_e32 v54, v54
	v_sub_f32_e32 v55, v56, v130
	v_exp_f32_e32 v55, v55
	v_sub_f32_e32 v57, v57, v130
	v_add_f32_e32 v56, 0, v52
	v_exp_f32_e32 v57, v57
	v_sub_f32_e32 v58, v58, v130
	v_add_f32_e32 v56, v53, v56
	v_exp_f32_e32 v58, v58
	v_sub_f32_e32 v59, v59, v130
	v_add_f32_e32 v56, v54, v56
	v_exp_f32_e32 v59, v59
	v_sub_f32_e32 v60, v60, v130
	v_add_f32_e32 v56, v55, v56
	v_exp_f32_e32 v60, v60
	v_sub_f32_e32 v61, v61, v130
	v_add_f32_e32 v56, v57, v56
	v_exp_f32_e32 v181, v61
	v_sub_f32_e32 v61, v62, v130
	v_add_f32_e32 v56, v58, v56
	v_exp_f32_e32 v183, v61
	v_sub_f32_e32 v61, v63, v130
	v_add_f32_e32 v56, v59, v56
	v_exp_f32_e32 v192, v61
	v_sub_f32_e32 v61, v64, v130
	v_add_f32_e32 v56, v60, v56
	v_exp_f32_e32 v193, v61
	v_sub_f32_e32 v61, v65, v130
	v_add_f32_e32 v56, v181, v56
	v_exp_f32_e32 v194, v61
	v_sub_f32_e32 v61, v66, v130
	v_add_f32_e32 v56, v183, v56
	v_exp_f32_e32 v195, v61
	v_sub_f32_e32 v61, v67, v130
	v_add_f32_e32 v56, v192, v56
	v_exp_f32_e32 v196, v61
	v_sub_f32_e32 v61, v68, v130
	v_add_f32_e32 v56, v193, v56
	v_exp_f32_e32 v197, v61
	v_sub_f32_e32 v61, v69, v130
	v_add_f32_e32 v56, v194, v56
	v_exp_f32_e32 v200, v61
	v_sub_f32_e32 v61, v70, v130
	v_add_f32_e32 v56, v195, v56
	v_exp_f32_e32 v201, v61
	v_sub_f32_e32 v61, v71, v130
	v_add_f32_e32 v56, v196, v56
	v_exp_f32_e32 v202, v61
	v_sub_f32_e32 v61, v131, v130
	v_add_f32_e32 v56, v197, v56
	v_exp_f32_e32 v203, v61
	v_sub_f32_e32 v61, v132, v130
	v_add_f32_e32 v56, v200, v56
	v_exp_f32_e32 v204, v61
	v_sub_f32_e32 v61, v133, v130
	v_add_f32_e32 v56, v201, v56
	v_exp_f32_e32 v205, v61
	v_sub_f32_e32 v61, v134, v130
	v_add_f32_e32 v56, v202, v56
	v_exp_f32_e32 v206, v61
	v_sub_f32_e32 v61, v135, v130
	v_add_f32_e32 v56, v203, v56
	v_exp_f32_e32 v207, v61
	v_sub_f32_e32 v61, v136, v130
	v_add_f32_e32 v56, v204, v56
	v_exp_f32_e32 v208, v61
	v_sub_f32_e32 v61, v137, v130
	v_add_f32_e32 v56, v205, v56
	v_exp_f32_e32 v209, v61
	v_sub_f32_e32 v61, v142, v130
	v_add_f32_e32 v56, v206, v56
	v_exp_f32_e32 v210, v61
	v_sub_f32_e32 v61, v143, v130
	v_add_f32_e32 v56, v207, v56
	v_exp_f32_e32 v211, v61
	v_sub_f32_e32 v61, v144, v130
	v_add_f32_e32 v56, v208, v56
	v_exp_f32_e32 v144, v61
	v_sub_f32_e32 v61, v145, v130
	v_add_f32_e32 v56, v209, v56
	v_exp_f32_e32 v145, v61
	v_sub_f32_e32 v61, v146, v130
	v_add_f32_e32 v56, v210, v56
	v_exp_f32_e32 v146, v61
	v_sub_f32_e32 v61, v147, v130
	v_add_f32_e32 v56, v211, v56
	v_exp_f32_e32 v147, v61
	v_sub_f32_e32 v61, v138, v130
	v_add_f32_e32 v56, v144, v56
	v_exp_f32_e32 v132, v61
	v_sub_f32_e32 v61, v139, v130
	v_add_f32_e32 v56, v145, v56
	v_exp_f32_e32 v133, v61
	v_sub_f32_e32 v61, v140, v130
	v_add_f32_e32 v56, v146, v56
	v_exp_f32_e32 v134, v61
	v_sub_f32_e32 v61, v141, v130
	v_add_f32_e32 v56, v147, v56
	v_exp_f32_e32 v135, v61
	v_sub_f32_e32 v48, v48, v130
	v_add_f32_e32 v56, v132, v56
	v_exp_f32_e32 v136, v48
	v_sub_f32_e32 v48, v49, v130
	v_add_f32_e32 v56, v133, v56
	v_exp_f32_e32 v137, v48
	v_sub_f32_e32 v48, v50, v130
	v_add_f32_e32 v56, v134, v56
	v_exp_f32_e32 v138, v48
	v_sub_f32_e32 v48, v51, v130
	v_add_f32_e32 v56, v135, v56
	v_exp_f32_e32 v139, v48
	v_add_f32_e32 v48, v136, v56
	v_add_f32_e32 v48, v137, v48
	v_add_f32_e32 v48, v138, v48
	v_add_f32_e32 v48, v139, v48
	v_mov_b32_e32 v49, v48
	s_nop 1
	v_permlane16_swap_b32 v48, v49
	v_cvt_pk_bf16_f32 v176, v52, v53
	v_cvt_pk_bf16_f32 v177, v54, v55
	v_cvt_pk_bf16_f32 v178, v57, v58
	v_cvt_pk_bf16_f32 v179, v59, v60
	s_waitcnt lgkmcnt(0)
	v_add_f32_e32 v48, v48, v49
	v_mov_b32_e32 v49, v48
	s_nop 1
	v_permlane32_swap_b32 v48, v49
	s_waitcnt lgkmcnt(0)
	v_add_f32_e32 v131, v48, v49
	s_cmp_eq_u32 s99, 1
	s_cbranch_scc1 .Lstg_p2_a
	s_barrier
.Lstg_p2_a:
	v_add_u32_e32 v48, s38, v88
	ds_read_b64_tr_b16 v[140:141], v48 offset:0
	ds_read_b64_tr_b16 v[142:143], v48 offset:0x440
	ds_read_b64_tr_b16 v[148:149], v48 offset:32
	ds_read_b64_tr_b16 v[150:151], v48 offset:0x460
	ds_read_b64_tr_b16 v[152:153], v48 offset:64
	ds_read_b64_tr_b16 v[154:155], v48 offset:0x480
	ds_read_b64_tr_b16 v[156:157], v48 offset:0x60
	ds_read_b64_tr_b16 v[158:159], v48 offset:0x4a0
	ds_read_b64_tr_b16 v[160:161], v48 offset:0x80
	ds_read_b64_tr_b16 v[162:163], v48 offset:0x4c0
	ds_read_b64_tr_b16 v[164:165], v48 offset:0xa0
	ds_read_b64_tr_b16 v[166:167], v48 offset:0x4e0
	ds_read_b64_tr_b16 v[168:169], v48 offset:0xc0
	ds_read_b64_tr_b16 v[170:171], v48 offset:0x500
	ds_read_b64_tr_b16 v[172:173], v48 offset:0xe0
	ds_read_b64_tr_b16 v[174:175], v48 offset:0x520
	s_waitcnt lgkmcnt(0)
	v_add_u32_e32 v198, s33, v88
	ds_read_b64_tr_b16 v[184:185], v198 offset:0
	ds_read_b64_tr_b16 v[186:187], v198 offset:0x440
	ds_read_b64_tr_b16 v[188:189], v198 offset:32
	ds_read_b64_tr_b16 v[190:191], v198 offset:0x460
	ds_read_b64_tr_b16 v[68:69], v198 offset:64
	ds_read_b64_tr_b16 v[70:71], v198 offset:0x480
	ds_read_b64_tr_b16 v[64:65], v198 offset:0x60
	ds_read_b64_tr_b16 v[66:67], v198 offset:0x4a0
	ds_read_b64_tr_b16 v[60:61], v198 offset:0x80
	ds_read_b64_tr_b16 v[62:63], v198 offset:0x4c0
	ds_read_b64_tr_b16 v[56:57], v198 offset:0xa0
	ds_read_b64_tr_b16 v[58:59], v198 offset:0x4e0
	ds_read_b64_tr_b16 v[52:53], v198 offset:0xc0
	ds_read_b64_tr_b16 v[54:55], v198 offset:0x500
	ds_read_b64_tr_b16 v[48:49], v198 offset:0xe0
	ds_read_b64_tr_b16 v[50:51], v198 offset:0x520
	s_waitcnt lgkmcnt(0)
	v_mfma_f32_16x16x32_bf16 v[140:143], v[140:143], v[176:179], 0
	v_mfma_f32_16x16x32_bf16 v[148:151], v[148:151], v[176:179], 0
	v_mfma_f32_16x16x32_bf16 v[152:155], v[152:155], v[176:179], 0
	v_mfma_f32_16x16x32_bf16 v[156:159], v[156:159], v[176:179], 0
	v_mfma_f32_16x16x32_bf16 v[160:163], v[160:163], v[176:179], 0
	v_mfma_f32_16x16x32_bf16 v[164:167], v[164:167], v[176:179], 0
	v_mfma_f32_16x16x32_bf16 v[168:171], v[168:171], v[176:179], 0
	v_mfma_f32_16x16x32_bf16 v[172:175], v[172:175], v[176:179], 0
	v_cvt_pk_bf16_f32 v176, v181, v183
	v_cvt_pk_bf16_f32 v177, v192, v193
	v_cvt_pk_bf16_f32 v178, v194, v195
	v_cvt_pk_bf16_f32 v179, v196, v197
	s_nop 1
	v_mfma_f32_16x16x32_bf16 v[140:143], v[184:187], v[176:179], v[140:143]
	v_add_u32_e32 v181, s2, v88
	ds_read_b64_tr_b16 v[184:185], v181 offset:0
	ds_read_b64_tr_b16 v[186:187], v181 offset:0x440
	v_mfma_f32_16x16x32_bf16 v[148:151], v[188:191], v[176:179], v[148:151]
	ds_read_b64_tr_b16 v[188:189], v181 offset:32
	ds_read_b64_tr_b16 v[190:191], v181 offset:0x460
	ds_read_b64_tr_b16 v[192:193], v181 offset:64
	ds_read_b64_tr_b16 v[194:195], v181 offset:0x480
	v_mfma_f32_16x16x32_bf16 v[68:71], v[68:71], v[176:179], v[152:155]
	ds_read_b64_tr_b16 v[152:153], v181 offset:0x60
	ds_read_b64_tr_b16 v[154:155], v181 offset:0x4a0
	v_cvt_pk_bf16_f32 v200, v200, v201
	v_mfma_f32_16x16x32_bf16 v[64:67], v[64:67], v[176:179], v[156:159]
	ds_read_b64_tr_b16 v[156:157], v181 offset:0x80
	ds_read_b64_tr_b16 v[158:159], v181 offset:0x4c0
	ds_read_b64_tr_b16 v[196:197], v181 offset:0xa0
	ds_read_b64_tr_b16 v[198:199], v181 offset:0x4e0
	v_mfma_f32_16x16x32_bf16 v[60:63], v[60:63], v[176:179], v[160:163]
	ds_read_b64_tr_b16 v[160:161], v181 offset:0xc0
	ds_read_b64_tr_b16 v[162:163], v181 offset:0x500
	v_cvt_pk_bf16_f32 v201, v202, v203
	v_mfma_f32_16x16x32_bf16 v[56:59], v[56:59], v[176:179], v[164:167]
	ds_read_b64_tr_b16 v[164:165], v181 offset:0xe0
	ds_read_b64_tr_b16 v[166:167], v181 offset:0x520
	s_waitcnt lgkmcnt(0)
	v_mfma_f32_16x16x32_bf16 v[48:51], v[48:51], v[176:179], v[172:175]
	v_cvt_pk_bf16_f32 v202, v204, v205
	v_cvt_pk_bf16_f32 v203, v206, v207
	v_mfma_f32_16x16x32_bf16 v[52:55], v[52:55], v[176:179], v[168:171]
	v_add_u32_e32 v181, s41, v88
	ds_read_b64_tr_b16 v[168:169], v181 offset:0
	ds_read_b64_tr_b16 v[170:171], v181 offset:0x440
	ds_read_b64_tr_b16 v[172:173], v181 offset:32
	ds_read_b64_tr_b16 v[174:175], v181 offset:0x460
	ds_read_b64_tr_b16 v[176:177], v181 offset:64
	ds_read_b64_tr_b16 v[178:179], v181 offset:0x480
	v_mfma_f32_16x16x32_bf16 v[140:143], v[184:187], v[200:203], v[140:143]
	ds_read_b64_tr_b16 v[184:185], v181 offset:0x60
	ds_read_b64_tr_b16 v[186:187], v181 offset:0x4a0
	v_mfma_f32_16x16x32_bf16 v[64:67], v[152:155], v[200:203], v[64:67]
	ds_read_b64_tr_b16 v[152:153], v181 offset:0x80
	ds_read_b64_tr_b16 v[154:155], v181 offset:0x4c0
	v_mfma_f32_16x16x32_bf16 v[148:151], v[188:191], v[200:203], v[148:151]
	ds_read_b64_tr_b16 v[188:189], v181 offset:0xa0
	ds_read_b64_tr_b16 v[190:191], v181 offset:0x4e0
	v_mfma_f32_16x16x32_bf16 v[60:63], v[156:159], v[200:203], v[60:63]
	ds_read_b64_tr_b16 v[156:157], v181 offset:0xc0
	ds_read_b64_tr_b16 v[158:159], v181 offset:0x500
	v_mfma_f32_16x16x32_bf16 v[68:71], v[192:195], v[200:203], v[68:71]
	ds_read_b64_tr_b16 v[192:193], v181 offset:0xe0
	ds_read_b64_tr_b16 v[194:195], v181 offset:0x520
	s_waitcnt lgkmcnt(0)
	v_mfma_f32_16x16x32_bf16 v[48:51], v[164:167], v[200:203], v[48:51]
	v_mfma_f32_16x16x32_bf16 v[56:59], v[196:199], v[200:203], v[56:59]
	v_cvt_pk_bf16_f32 v196, v208, v209
	v_cvt_pk_bf16_f32 v197, v210, v211
	v_cvt_pk_bf16_f32 v198, v144, v145
	v_mfma_f32_16x16x32_bf16 v[52:55], v[160:163], v[200:203], v[52:55]
	v_cvt_pk_bf16_f32 v199, v146, v147
	v_add_u32_e32 v144, s40, v88
	ds_read_b64_tr_b16 v[160:161], v144 offset:0
	ds_read_b64_tr_b16 v[162:163], v144 offset:0x440
	ds_read_b64_tr_b16 v[164:165], v144 offset:32
	ds_read_b64_tr_b16 v[166:167], v144 offset:0x460
	s_nop 0
	v_mfma_f32_16x16x32_bf16 v[140:143], v[168:171], v[196:199], v[140:143]
	ds_read_b64_tr_b16 v[168:169], v144 offset:64
	ds_read_b64_tr_b16 v[170:171], v144 offset:0x480
	v_mfma_f32_16x16x32_bf16 v[148:151], v[172:175], v[196:199], v[148:151]
	ds_read_b64_tr_b16 v[172:173], v144 offset:0x60
	ds_read_b64_tr_b16 v[174:175], v144 offset:0x4a0
	v_mfma_f32_16x16x32_bf16 v[60:63], v[152:155], v[196:199], v[60:63]
	ds_read_b64_tr_b16 v[152:153], v144 offset:0x80
	ds_read_b64_tr_b16 v[154:155], v144 offset:0x4c0
	v_mfma_f32_16x16x32_bf16 v[68:71], v[176:179], v[196:199], v[68:71]
	ds_read_b64_tr_b16 v[176:177], v144 offset:0xa0
	ds_read_b64_tr_b16 v[178:179], v144 offset:0x4e0
	v_mfma_f32_16x16x32_bf16 v[64:67], v[184:187], v[196:199], v[64:67]
	ds_read_b64_tr_b16 v[184:185], v144 offset:0xc0
	ds_read_b64_tr_b16 v[186:187], v144 offset:0x500
	v_mfma_f32_16x16x32_bf16 v[52:55], v[156:159], v[196:199], v[52:55]
	ds_read_b64_tr_b16 v[156:157], v144 offset:0xe0
	ds_read_b64_tr_b16 v[158:159], v144 offset:0x520
	s_waitcnt lgkmcnt(0)
	v_mfma_f32_16x16x32_bf16 v[56:59], v[188:191], v[196:199], v[56:59]
	v_mfma_f32_16x16x32_bf16 v[188:191], v[192:195], v[196:199], v[48:51]
	v_cvt_pk_bf16_f32 v132, v132, v133
	v_cvt_pk_bf16_f32 v133, v134, v135
	v_cvt_pk_bf16_f32 v134, v136, v137
	v_cvt_pk_bf16_f32 v135, v138, v139
	v_rcp_f32_e32 v144, v131
	v_add_u32_e32 v48, s95, v129
	v_mfma_f32_16x16x32_bf16 v[136:139], v[160:163], v[132:135], v[140:143]
	v_ashrrev_i32_e32 v49, 31, v48
	v_lshl_add_u64 v[48:49], s[64:65], 0, v[48:49]
	v_lshlrev_b64 v[50:51], 11, v[48:49]
	v_mfma_f32_16x16x32_bf16 v[140:143], v[164:167], v[132:135], v[148:151]
	v_lshl_add_u64 v[146:147], v[78:79], 0, v[50:51]
	s_nop 2
	v_pk_mul_f32 v[50:51], v[144:145], v[136:137] op_sel_hi:[0,1]
	v_pk_mul_f32 v[136:137], v[144:145], v[138:139] op_sel_hi:[0,1]
	v_mfma_f32_16x16x32_bf16 v[68:71], v[168:171], v[132:135], v[68:71]
	v_cvt_pk_bf16_f32 v50, v50, v51
	v_cvt_pk_bf16_f32 v51, v136, v137
	global_store_dwordx2 v[146:147], v[50:51], off
	v_mfma_f32_16x16x32_bf16 v[64:67], v[172:175], v[132:135], v[64:67]
	v_mul_f32_e64 v50, v144, v140
	v_mul_f32_e64 v51, v144, v141
	v_pk_mul_f32 v[136:137], v[144:145], v[142:143] op_sel_hi:[0,1]
	v_cvt_pk_bf16_f32 v50, v50, v51
	v_cvt_pk_bf16_f32 v51, v136, v137
	v_mfma_f32_16x16x32_bf16 v[60:63], v[152:155], v[132:135], v[60:63]
	global_store_dwordx2 v[146:147], v[50:51], off offset:32
	v_pk_mul_f32 v[136:137], v[144:145], v[70:71] op_sel_hi:[0,1]
	v_mfma_f32_16x16x32_bf16 v[50:53], v[184:187], v[132:135], v[52:55]
	s_nop 2
	v_mul_f32_e64 v54, v144, v68
	v_mul_f32_e64 v55, v144, v69
	v_cvt_pk_bf16_f32 v54, v54, v55
	v_cvt_pk_bf16_f32 v55, v136, v137
	v_mfma_f32_16x16x32_bf16 v[56:59], v[176:179], v[132:135], v[56:59]
	global_store_dwordx2 v[146:147], v[54:55], off offset:64
	v_pk_mul_f32 v[54:55], v[144:145], v[64:65] op_sel_hi:[0,1]
	v_pk_mul_f32 v[64:65], v[144:145], v[66:67] op_sel_hi:[0,1]
	v_mfma_f32_16x16x32_bf16 v[68:71], v[156:159], v[132:135], v[188:191]
	v_cvt_pk_bf16_f32 v54, v54, v55
	v_cvt_pk_bf16_f32 v55, v64, v65
	global_store_dwordx2 v[146:147], v[54:55], off offset:96
	v_pk_mul_f32 v[54:55], v[144:145], v[60:61] op_sel_hi:[0,1]
	v_pk_mul_f32 v[60:61], v[144:145], v[62:63] op_sel_hi:[0,1]
	v_pk_mul_f32 v[50:51], v[144:145], v[50:51] op_sel_hi:[0,1]
	v_pk_mul_f32 v[52:53], v[144:145], v[52:53] op_sel_hi:[0,1]
	v_cvt_pk_bf16_f32 v54, v54, v55
	v_cvt_pk_bf16_f32 v55, v60, v61
	v_cvt_pk_bf16_f32 v50, v50, v51
	v_cvt_pk_bf16_f32 v51, v52, v53
	global_store_dwordx2 v[146:147], v[54:55], off offset:128
	v_pk_mul_f32 v[54:55], v[144:145], v[56:57] op_sel_hi:[0,1]
	v_pk_mul_f32 v[56:57], v[144:145], v[58:59] op_sel_hi:[0,1]
	global_store_dwordx2 v[146:147], v[50:51], off offset:192
	v_pk_mul_f32 v[50:51], v[144:145], v[68:69] op_sel_hi:[0,1]
	v_pk_mul_f32 v[52:53], v[144:145], v[70:71] op_sel_hi:[0,1]
	v_cvt_pk_bf16_f32 v54, v54, v55
	v_cvt_pk_bf16_f32 v55, v56, v57
	v_cvt_pk_bf16_f32 v50, v50, v51
	v_cvt_pk_bf16_f32 v51, v52, v53
	global_store_dwordx2 v[146:147], v[54:55], off offset:160
	global_store_dwordx2 v[146:147], v[50:51], off offset:224
	s_and_saveexec_b64 s[40:41], s[0:1]
	s_cbranch_execz .LBB0_256
	v_log_f32_e32 v50, v131
	v_lshlrev_b64 v[48:49], 5, v[48:49]
	v_lshl_add_u64 v[48:49], s[88:89], 0, v[48:49]
	v_add_f32_e32 v50, v130, v50
	v_mul_f32_e32 v50, 0x3f317218, v50
	global_store_dword v[48:49], v50, off

.Lpadskip_1:
	s_branch .Lpadskip_3
	s_nop 0
	s_nop 0
	s_nop 0
	s_nop 0
	s_nop 0
	s_nop 0
	s_nop 0
	s_nop 0
	s_nop 0
	s_nop 0
	s_nop 0
	s_nop 0
	s_nop 0
	s_nop 0
	s_nop 0
	s_nop 0
	s_nop 0
	s_nop 0
	s_nop 0
	s_nop 0
	s_nop 0
	s_nop 0
	s_nop 0
	s_nop 0
	s_nop 0
	s_nop 0
	s_nop 0
	s_nop 0
	s_nop 0
	s_nop 0
	s_nop 0
	s_nop 0
	s_nop 0
	s_nop 0
	s_nop 0
	s_nop 0
	s_nop 0
	s_nop 0
	s_nop 0
	s_nop 0
	s_nop 0
	s_nop 0
	s_nop 0
	s_nop 0
	s_nop 0
	s_nop 0
	s_nop 0
	s_nop 0
	s_nop 0
	s_nop 0
	s_nop 0
	s_nop 0
	s_nop 0
	s_nop 0
	s_nop 0
	s_nop 0
	s_nop 0
	s_nop 0
	s_nop 0
.Lpadskip_3:
	s_branch .Lpadskip_4
	s_nop 0
	s_nop 0
	s_nop 0
	s_nop 0
	s_nop 0
	s_nop 0
	s_nop 0
	s_nop 0
	s_nop 0
	s_nop 0
	s_nop 0
	s_nop 0
	s_nop 0
	s_nop 0
	s_nop 0
	s_nop 0
	s_nop 0
	s_nop 0
	s_nop 0
	s_nop 0
	s_nop 0
	s_nop 0
	s_nop 0
	s_nop 0
	s_nop 0
	s_nop 0
	s_nop 0
	s_nop 0
	s_nop 0
	s_nop 0
	s_nop 0
	s_nop 0
	s_nop 0
	s_nop 0
	s_nop 0
	s_nop 0
	s_nop 0
	s_nop 0
	s_nop 0
	s_nop 0
	s_nop 0
	s_nop 0
	s_nop 0
	s_nop 0
	s_nop 0
	s_nop 0
	s_nop 0
	s_nop 0
	s_nop 0
	s_nop 0
	s_nop 0
	s_nop 0
	s_nop 0
	s_nop 0
	s_nop 0
	s_nop 0
.Lpadskip_4:
.LBB0_402:
	s_add_i32 s36, s93, s33
	s_lshl_b32 s3, s3, 12
	v_lshl_add_u64 v[16:17], v[12:13], 0, s[70:71]
	s_mov_b32 m0, s36
	s_add_i32 s19, s36, 0x2000
	s_lshl_b32 s10, s2, 13
	s_and_b32 s11, s3, 0x3000
	s_waitcnt vmcnt(4)
	s_barrier
	global_load_lds_dwordx4 v[16:17], off
	v_lshl_add_u64 v[16:17], v[10:11], 0, s[70:71]
	s_mov_b32 m0, s19
	s_add_i32 s16, s41, 0x8000
	s_add_i32 s15, s41, 0xa000
	global_load_lds_dwordx4 v[16:17], off
	v_lshl_add_u64 v[16:17], v[6:7], 0, s[70:71]
	s_mov_b32 m0, s16
	s_add_u32 s6, s4, 0x10080
	global_load_lds_dwordx4 v[16:17], off
	v_lshl_add_u64 v[16:17], v[8:9], 0, s[70:71]
	s_mov_b32 m0, s15
	s_addc_u32 s7, s5, 0
	s_add_i32 s2, s94, s33
	global_load_lds_dwordx4 v[16:17], off
	v_lshl_add_u64 v[16:17], s[6:7], 0, v[128:129]
	s_mov_b32 m0, s2
	s_add_i32 s3, s2, 0x2000
	global_load_lds_dwordx4 v[16:17], off
	v_lshl_add_u64 v[16:17], s[6:7], 0, v[4:5]
	s_mov_b32 m0, s3
	v_and_b32_e32 v15, 15, v14
	global_load_lds_dwordx4 v[16:17], off
	v_and_b32_e32 v16, 48, v14
	v_lshlrev_b32_e32 v14, 2, v14
	v_lshlrev_b32_e32 v15, 6, v15
	v_and_b32_e32 v14, 32, v14
	v_or_b32_e32 v17, v15, v16
	v_bitop3_b32 v15, v15, v14, v16 bitop3:0x36
	v_or_b32_e32 v64, s11, v15
	s_add_i32 s43, 0, 0x10000
	v_bitop3_b32 v14, v17, s10, v14 bitop3:0xde
	v_add_u32_e32 v131, s43, v64
	s_waitcnt vmcnt(6)
	s_barrier
	s_add_u32 s48, s8, 0x10080
	v_add_u32_e32 v183, 0, v14
	ds_read_b128 v[14:17], v131
	ds_read_b128 v[18:21], v131 offset:1024
	ds_read_b128 v[22:25], v131 offset:2048
	ds_read_b128 v[26:29], v131 offset:3072
	s_addc_u32 s49, s9, 0
	s_add_i32 s50, 0, 0x14000
	s_add_u32 s12, s4, 0x10100
	s_addc_u32 s13, s5, 0
	s_add_u32 s10, s8, 0x10100
	s_addc_u32 s11, s9, 0
	s_add_u32 s6, s4, 0x10180
	v_add_u32_e32 v144, s50, v64
	s_addc_u32 s7, s5, 0
	s_add_i32 s17, s41, 0xc000
	v_lshl_add_u64 v[62:63], s[48:49], 0, v[0:1]
	s_mov_b32 m0, s17
	s_add_i32 s14, s41, 0xe000
	ds_read_b128 v[30:33], v183
	ds_read_b128 v[34:37], v183 offset:1024
	ds_read_b128 v[38:41], v183 offset:2048
	ds_read_b128 v[42:45], v183 offset:3072
	ds_read_b128 v[46:49], v183 offset:4096
	ds_read_b128 v[50:53], v183 offset:5120
	ds_read_b128 v[54:57], v183 offset:6144
	ds_read_b128 v[58:61], v183 offset:7168
	global_load_lds_dwordx4 v[62:63], off
	v_lshl_add_u64 v[62:63], s[48:49], 0, v[2:3]
	s_mov_b32 m0, s14
	v_add_u32_e32 v145, s93, v64
	global_load_lds_dwordx4 v[62:63], off
	s_waitcnt lgkmcnt(8)
	s_barrier
	s_waitcnt lgkmcnt(0)
	v_add_u32_e32 v146, s94, v64
	s_setprio 1
	s_waitcnt lgkmcnt(0)
	v_mfma_f32_16x16x32_bf16 v[62:65], v[14:17], v[30:33], 0
	v_mfma_f32_16x16x32_bf16 v[66:69], v[22:25], v[30:33], 0
	v_mfma_f32_16x16x32_bf16 v[70:73], v[14:17], v[38:41], 0
	v_mfma_f32_16x16x32_bf16 v[74:77], v[22:25], v[38:41], 0
	v_mfma_f32_16x16x32_bf16 v[78:81], v[14:17], v[46:49], 0
	v_mfma_f32_16x16x32_bf16 v[82:85], v[22:25], v[46:49], 0
	v_mfma_f32_16x16x32_bf16 v[86:89], v[14:17], v[54:57], 0
	v_mfma_f32_16x16x32_bf16 v[90:93], v[22:25], v[54:57], 0
	v_mfma_f32_16x16x32_bf16 v[62:65], v[18:21], v[34:37], v[62:65]
	v_mfma_f32_16x16x32_bf16 v[66:69], v[26:29], v[34:37], v[66:69]
	v_mfma_f32_16x16x32_bf16 v[70:73], v[18:21], v[42:45], v[70:73]
	v_mfma_f32_16x16x32_bf16 v[74:77], v[26:29], v[42:45], v[74:77]
	v_mfma_f32_16x16x32_bf16 v[78:81], v[18:21], v[50:53], v[78:81]
	v_mfma_f32_16x16x32_bf16 v[82:85], v[26:29], v[50:53], v[82:85]
	v_mfma_f32_16x16x32_bf16 v[86:89], v[18:21], v[58:61], v[86:89]
	v_mfma_f32_16x16x32_bf16 v[90:93], v[26:29], v[58:61], v[90:93]
	s_setprio 0
	s_barrier
	s_add_i32 s43, s43, s33
	v_lshl_add_u64 v[110:111], v[12:13], 0, s[72:73]
	s_mov_b32 m0, s43
	ds_read_b128 v[94:97], v144
	ds_read_b128 v[98:101], v144 offset:1024
	ds_read_b128 v[102:105], v144 offset:2048
	ds_read_b128 v[106:109], v144 offset:3072
	global_load_lds_dwordx4 v[110:111], off
	v_lshl_add_u64 v[110:111], v[10:11], 0, s[72:73]
	s_add_i32 m0, s43, 0x2000
	s_nop 0
	global_load_lds_dwordx4 v[110:111], off
	s_barrier
	s_waitcnt lgkmcnt(0)
	s_setprio 1
	s_waitcnt lgkmcnt(0)
	v_mfma_f32_16x16x32_bf16 v[110:113], v[94:97], v[30:33], 0
	v_mfma_f32_16x16x32_bf16 v[30:33], v[102:105], v[30:33], 0
	v_mfma_f32_16x16x32_bf16 v[110:113], v[98:101], v[34:37], v[110:113]
	v_mfma_f32_16x16x32_bf16 v[30:33], v[106:109], v[34:37], v[30:33]
	v_mfma_f32_16x16x32_bf16 v[34:37], v[94:97], v[38:41], 0
	v_mfma_f32_16x16x32_bf16 v[38:41], v[102:105], v[38:41], 0
	v_mfma_f32_16x16x32_bf16 v[34:37], v[98:101], v[42:45], v[34:37]
	v_mfma_f32_16x16x32_bf16 v[38:41], v[106:109], v[42:45], v[38:41]
	v_mfma_f32_16x16x32_bf16 v[42:45], v[94:97], v[46:49], 0
	v_mfma_f32_16x16x32_bf16 v[46:49], v[102:105], v[46:49], 0
	v_mfma_f32_16x16x32_bf16 v[42:45], v[98:101], v[50:53], v[42:45]
	v_mfma_f32_16x16x32_bf16 v[46:49], v[106:109], v[50:53], v[46:49]
	v_mfma_f32_16x16x32_bf16 v[50:53], v[94:97], v[54:57], 0
	v_mfma_f32_16x16x32_bf16 v[54:57], v[102:105], v[54:57], 0
	v_mfma_f32_16x16x32_bf16 v[50:53], v[98:101], v[58:61], v[50:53]
	v_mfma_f32_16x16x32_bf16 v[54:57], v[106:109], v[58:61], v[54:57]
	s_setprio 0
	s_mov_b32 m0, s41
	v_lshl_add_u64 v[126:127], v[6:7], 0, s[72:73]
	s_barrier
	ds_read_b128 v[58:61], v183 offset:16384
	ds_read_b128 v[114:117], v183 offset:17408
	ds_read_b128 v[118:121], v183 offset:18432
	ds_read_b128 v[122:125], v183 offset:19456
	ds_read_b128 v[132:135], v183 offset:20480
	ds_read_b128 v[136:139], v183 offset:21504
	ds_read_b128 v[140:143], v183 offset:22528
	ds_read_b128 v[152:155], v183 offset:23552
	global_load_lds_dwordx4 v[126:127], off
	v_lshl_add_u64 v[126:127], v[8:9], 0, s[72:73]
	s_mov_b32 m0, s42
	s_nop 0
	global_load_lds_dwordx4 v[126:127], off
	s_barrier
	s_waitcnt lgkmcnt(0)
	s_setprio 1
	s_waitcnt lgkmcnt(0)
	v_mfma_f32_16x16x32_bf16 v[156:159], v[14:17], v[58:61], 0
	v_mfma_f32_16x16x32_bf16 v[164:167], v[14:17], v[118:121], 0
	v_mfma_f32_16x16x32_bf16 v[172:175], v[14:17], v[132:135], 0
	v_mfma_f32_16x16x32_bf16 v[14:17], v[14:17], v[140:143], 0
	v_mfma_f32_16x16x32_bf16 v[156:159], v[18:21], v[114:117], v[156:159]
	v_mfma_f32_16x16x32_bf16 v[164:167], v[18:21], v[122:125], v[164:167]
	v_mfma_f32_16x16x32_bf16 v[172:175], v[18:21], v[136:139], v[172:175]
	v_mfma_f32_16x16x32_bf16 v[14:17], v[18:21], v[152:155], v[14:17]
	v_mfma_f32_16x16x32_bf16 v[18:21], v[22:25], v[140:143], 0
	v_mfma_f32_16x16x32_bf16 v[160:163], v[22:25], v[58:61], 0
	v_mfma_f32_16x16x32_bf16 v[168:171], v[22:25], v[118:121], 0
	v_mfma_f32_16x16x32_bf16 v[176:179], v[22:25], v[132:135], 0
	v_mfma_f32_16x16x32_bf16 v[18:21], v[26:29], v[152:155], v[18:21]
	v_mfma_f32_16x16x32_bf16 v[160:163], v[26:29], v[114:117], v[160:163]
	v_mfma_f32_16x16x32_bf16 v[168:171], v[26:29], v[122:125], v[168:171]
	v_mfma_f32_16x16x32_bf16 v[176:179], v[26:29], v[136:139], v[176:179]
	s_setprio 0
	s_barrier
	s_add_i32 s33, s50, s33
	v_lshl_add_u64 v[22:23], s[12:13], 0, v[128:129]
	s_mov_b32 m0, s33
	s_nop 0
	global_load_lds_dwordx4 v[22:23], off
	v_lshl_add_u64 v[22:23], s[12:13], 0, v[4:5]
	s_add_i32 m0, s33, 0x2000
	s_nop 0
	global_load_lds_dwordx4 v[22:23], off
	s_waitcnt vmcnt(6)
	s_barrier
	s_setprio 1
	v_mfma_f32_16x16x32_bf16 v[22:25], v[94:97], v[58:61], 0
	v_mfma_f32_16x16x32_bf16 v[26:29], v[102:105], v[58:61], 0
	v_mfma_f32_16x16x32_bf16 v[22:25], v[98:101], v[114:117], v[22:25]
	v_mfma_f32_16x16x32_bf16 v[26:29], v[106:109], v[114:117], v[26:29]
	v_mfma_f32_16x16x32_bf16 v[58:61], v[94:97], v[118:121], 0
	v_mfma_f32_16x16x32_bf16 v[114:117], v[102:105], v[118:121], 0
	v_mfma_f32_16x16x32_bf16 v[118:121], v[94:97], v[132:135], 0
	v_mfma_f32_16x16x32_bf16 v[94:97], v[94:97], v[140:143], 0
	v_mfma_f32_16x16x32_bf16 v[58:61], v[98:101], v[122:125], v[58:61]
	v_mfma_f32_16x16x32_bf16 v[114:117], v[106:109], v[122:125], v[114:117]
	v_mfma_f32_16x16x32_bf16 v[118:121], v[98:101], v[136:139], v[118:121]
	v_mfma_f32_16x16x32_bf16 v[122:125], v[102:105], v[132:135], 0
	v_mfma_f32_16x16x32_bf16 v[94:97], v[98:101], v[152:155], v[94:97]
	v_mfma_f32_16x16x32_bf16 v[98:101], v[102:105], v[140:143], 0
	v_mfma_f32_16x16x32_bf16 v[122:125], v[106:109], v[136:139], v[122:125]
	v_mfma_f32_16x16x32_bf16 v[98:101], v[106:109], v[152:155], v[98:101]
	s_setprio 0
	s_barrier
	ds_read_b128 v[102:105], v145
	ds_read_b128 v[106:109], v145 offset:1024
	ds_read_b128 v[132:135], v145 offset:2048
	ds_read_b128 v[136:139], v145 offset:3072
	s_mov_b32 m0, s40
	v_lshl_add_u64 v[126:127], s[10:11], 0, v[0:1]
	ds_read_b128 v[140:143], v183 offset:32768
	ds_read_b128 v[152:155], v183 offset:33792
	ds_read_b128 v[184:187], v183 offset:34816
	ds_read_b128 v[188:191], v183 offset:35840
	ds_read_b128 v[192:195], v183 offset:36864
	ds_read_b128 v[196:199], v183 offset:37888
	ds_read_b128 v[200:203], v183 offset:38912
	ds_read_b128 v[204:207], v183 offset:39936
	global_load_lds_dwordx4 v[126:127], off
	v_lshl_add_u64 v[126:127], s[10:11], 0, v[2:3]
	s_mov_b32 m0, s18
	s_nop 0
	global_load_lds_dwordx4 v[126:127], off
	s_waitcnt lgkmcnt(8)
	s_barrier
	s_waitcnt lgkmcnt(0)
	s_setprio 1
	s_waitcnt lgkmcnt(0)
	v_mfma_f32_16x16x32_bf16 v[62:65], v[102:105], v[140:143], v[62:65]
	v_mfma_f32_16x16x32_bf16 v[66:69], v[132:135], v[140:143], v[66:69]
	v_mfma_f32_16x16x32_bf16 v[70:73], v[102:105], v[184:187], v[70:73]
	v_mfma_f32_16x16x32_bf16 v[74:77], v[132:135], v[184:187], v[74:77]
	v_mfma_f32_16x16x32_bf16 v[78:81], v[102:105], v[192:195], v[78:81]
	v_mfma_f32_16x16x32_bf16 v[82:85], v[132:135], v[192:195], v[82:85]
	v_mfma_f32_16x16x32_bf16 v[86:89], v[102:105], v[200:203], v[86:89]
	v_mfma_f32_16x16x32_bf16 v[90:93], v[132:135], v[200:203], v[90:93]
	v_mfma_f32_16x16x32_bf16 v[62:65], v[106:109], v[152:155], v[62:65]
	v_mfma_f32_16x16x32_bf16 v[66:69], v[136:139], v[152:155], v[66:69]
	v_mfma_f32_16x16x32_bf16 v[70:73], v[106:109], v[188:191], v[70:73]
	v_mfma_f32_16x16x32_bf16 v[74:77], v[136:139], v[188:191], v[74:77]
	v_mfma_f32_16x16x32_bf16 v[78:81], v[106:109], v[196:199], v[78:81]
	v_mfma_f32_16x16x32_bf16 v[82:85], v[136:139], v[196:199], v[82:85]
	v_mfma_f32_16x16x32_bf16 v[86:89], v[106:109], v[204:207], v[86:89]
	v_mfma_f32_16x16x32_bf16 v[90:93], v[136:139], v[204:207], v[90:93]
	s_setprio 0
	s_barrier
	s_mov_b32 m0, s36
	v_lshl_add_u64 v[12:13], v[12:13], 0, s[76:77]
	ds_read_b128 v[208:211], v146
	ds_read_b128 v[212:215], v146 offset:1024
	ds_read_b128 v[216:219], v146 offset:2048
	ds_read_b128 v[220:223], v146 offset:3072
	global_load_lds_dwordx4 v[12:13], off
	v_lshl_add_u64 v[10:11], v[10:11], 0, s[76:77]
	s_mov_b32 m0, s19
	s_nop 0
	global_load_lds_dwordx4 v[10:11], off
	s_barrier
	s_waitcnt lgkmcnt(0)
	s_setprio 1
	s_waitcnt lgkmcnt(0)
	v_mfma_f32_16x16x32_bf16 v[10:13], v[208:211], v[140:143], v[110:113]
	v_mfma_f32_16x16x32_bf16 v[30:33], v[216:219], v[140:143], v[30:33]
	v_mfma_f32_16x16x32_bf16 v[34:37], v[208:211], v[184:187], v[34:37]
	v_mfma_f32_16x16x32_bf16 v[38:41], v[216:219], v[184:187], v[38:41]
	v_mfma_f32_16x16x32_bf16 v[42:45], v[208:211], v[192:195], v[42:45]
	v_mfma_f32_16x16x32_bf16 v[46:49], v[216:219], v[192:195], v[46:49]
	v_mfma_f32_16x16x32_bf16 v[50:53], v[208:211], v[200:203], v[50:53]
	v_mfma_f32_16x16x32_bf16 v[54:57], v[216:219], v[200:203], v[54:57]
	v_mfma_f32_16x16x32_bf16 v[10:13], v[212:215], v[152:155], v[10:13]
	v_mfma_f32_16x16x32_bf16 v[30:33], v[220:223], v[152:155], v[30:33]
	v_mfma_f32_16x16x32_bf16 v[34:37], v[212:215], v[188:191], v[34:37]
	v_mfma_f32_16x16x32_bf16 v[38:41], v[220:223], v[188:191], v[38:41]
	v_mfma_f32_16x16x32_bf16 v[42:45], v[212:215], v[196:199], v[42:45]
	v_mfma_f32_16x16x32_bf16 v[46:49], v[220:223], v[196:199], v[46:49]
	v_mfma_f32_16x16x32_bf16 v[50:53], v[212:215], v[204:207], v[50:53]
	v_mfma_f32_16x16x32_bf16 v[54:57], v[220:223], v[204:207], v[54:57]
	s_setprio 0
	s_mov_b32 m0, s16
	v_lshl_add_u64 v[6:7], v[6:7], 0, s[76:77]
	s_barrier
	ds_read_b128 v[110:113], v183 offset:49152
	ds_read_b128 v[140:143], v183 offset:50176
	ds_read_b128 v[152:155], v183 offset:51200
	ds_read_b128 v[184:187], v183 offset:52224
	ds_read_b128 v[188:191], v183 offset:53248
	ds_read_b128 v[192:195], v183 offset:54272
	ds_read_b128 v[196:199], v183 offset:55296
	ds_read_b128 v[200:203], v183 offset:56320
	global_load_lds_dwordx4 v[6:7], off
	v_lshl_add_u64 v[6:7], v[8:9], 0, s[76:77]
	s_mov_b32 m0, s15
	s_nop 0
	global_load_lds_dwordx4 v[6:7], off
	s_barrier
	s_waitcnt lgkmcnt(0)
	s_setprio 1
	s_waitcnt lgkmcnt(0)
	v_mfma_f32_16x16x32_bf16 v[6:9], v[102:105], v[110:113], v[156:159]
	v_mfma_f32_16x16x32_bf16 v[14:17], v[102:105], v[196:199], v[14:17]
	v_mfma_f32_16x16x32_bf16 v[18:21], v[132:135], v[196:199], v[18:21]
	v_mfma_f32_16x16x32_bf16 v[6:9], v[106:109], v[140:143], v[6:9]
	v_mfma_f32_16x16x32_bf16 v[156:159], v[132:135], v[110:113], v[160:163]
	v_mfma_f32_16x16x32_bf16 v[160:163], v[102:105], v[152:155], v[164:167]
	v_mfma_f32_16x16x32_bf16 v[164:167], v[132:135], v[152:155], v[168:171]
	v_mfma_f32_16x16x32_bf16 v[168:171], v[102:105], v[188:191], v[172:175]
	v_mfma_f32_16x16x32_bf16 v[172:175], v[132:135], v[188:191], v[176:179]
	v_mfma_f32_16x16x32_bf16 v[14:17], v[106:109], v[200:203], v[14:17]
	v_mfma_f32_16x16x32_bf16 v[18:21], v[136:139], v[200:203], v[18:21]
	v_mfma_f32_16x16x32_bf16 v[156:159], v[136:139], v[140:143], v[156:159]
	v_mfma_f32_16x16x32_bf16 v[160:163], v[106:109], v[184:187], v[160:163]
	v_mfma_f32_16x16x32_bf16 v[164:167], v[136:139], v[184:187], v[164:167]
	v_mfma_f32_16x16x32_bf16 v[168:171], v[106:109], v[192:195], v[168:171]
	v_mfma_f32_16x16x32_bf16 v[172:175], v[136:139], v[192:195], v[172:175]
	s_setprio 0
	s_barrier
	s_mov_b32 m0, s2
	v_lshl_add_u64 v[102:103], s[6:7], 0, v[128:129]
	global_load_lds_dwordx4 v[102:103], off
	v_lshl_add_u64 v[4:5], s[6:7], 0, v[4:5]
	s_mov_b32 m0, s3
	s_nop 0
	global_load_lds_dwordx4 v[4:5], off
	s_waitcnt vmcnt(6)
	s_barrier
	s_setprio 1
	v_mfma_f32_16x16x32_bf16 v[22:25], v[208:211], v[110:113], v[22:25]
	v_mfma_f32_16x16x32_bf16 v[26:29], v[216:219], v[110:113], v[26:29]
	v_mfma_f32_16x16x32_bf16 v[58:61], v[208:211], v[152:155], v[58:61]
	v_mfma_f32_16x16x32_bf16 v[102:105], v[216:219], v[152:155], v[114:117]
	v_mfma_f32_16x16x32_bf16 v[106:109], v[208:211], v[188:191], v[118:121]
	v_mfma_f32_16x16x32_bf16 v[110:113], v[216:219], v[188:191], v[122:125]
	v_mfma_f32_16x16x32_bf16 v[94:97], v[208:211], v[196:199], v[94:97]
	v_mfma_f32_16x16x32_bf16 v[98:101], v[216:219], v[196:199], v[98:101]
	v_mfma_f32_16x16x32_bf16 v[22:25], v[212:215], v[140:143], v[22:25]
	v_mfma_f32_16x16x32_bf16 v[26:29], v[220:223], v[140:143], v[26:29]
	v_mfma_f32_16x16x32_bf16 v[58:61], v[212:215], v[184:187], v[58:61]
	v_mfma_f32_16x16x32_bf16 v[102:105], v[220:223], v[184:187], v[102:105]
	v_mfma_f32_16x16x32_bf16 v[106:109], v[212:215], v[192:195], v[106:109]
	v_mfma_f32_16x16x32_bf16 v[110:113], v[220:223], v[192:195], v[110:113]
	v_mfma_f32_16x16x32_bf16 v[94:97], v[212:215], v[200:203], v[94:97]
	v_mfma_f32_16x16x32_bf16 v[98:101], v[220:223], v[200:203], v[98:101]
	s_setprio 0
	s_add_u32 s2, s8, 0x10180
	s_addc_u32 s3, s9, 0
	s_mov_b32 m0, s17
	v_lshl_add_u64 v[0:1], s[2:3], 0, v[0:1]
	s_barrier
	ds_read_b128 v[114:117], v131
	ds_read_b128 v[118:121], v131 offset:1024
	ds_read_b128 v[122:125], v131 offset:2048
	ds_read_b128 v[132:135], v131 offset:3072
	ds_read_b128 v[136:139], v183
	ds_read_b128 v[140:143], v183 offset:1024
	ds_read_b128 v[152:155], v183 offset:2048
	ds_read_b128 v[176:179], v183 offset:3072
	ds_read_b128 v[184:187], v183 offset:4096
	ds_read_b128 v[188:191], v183 offset:5120
	ds_read_b128 v[192:195], v183 offset:6144
	ds_read_b128 v[196:199], v183 offset:7168
	global_load_lds_dwordx4 v[0:1], off
	v_lshl_add_u64 v[0:1], s[2:3], 0, v[2:3]
	s_mov_b32 m0, s14
	s_nop 0
	global_load_lds_dwordx4 v[0:1], off
	s_barrier
	s_waitcnt lgkmcnt(0)
	s_setprio 1
	s_waitcnt lgkmcnt(0)
	v_mfma_f32_16x16x32_bf16 v[0:3], v[114:117], v[136:139], v[62:65]
	v_mfma_f32_16x16x32_bf16 v[62:65], v[122:125], v[136:139], v[66:69]
	v_mfma_f32_16x16x32_bf16 v[66:69], v[114:117], v[152:155], v[70:73]
	v_mfma_f32_16x16x32_bf16 v[70:73], v[122:125], v[152:155], v[74:77]
	v_mfma_f32_16x16x32_bf16 v[74:77], v[114:117], v[184:187], v[78:81]
	v_mfma_f32_16x16x32_bf16 v[78:81], v[122:125], v[184:187], v[82:85]
	v_mfma_f32_16x16x32_bf16 v[82:85], v[114:117], v[192:195], v[86:89]
	v_mfma_f32_16x16x32_bf16 v[0:3], v[118:121], v[140:143], v[0:3]
	v_mfma_f32_16x16x32_bf16 v[62:65], v[132:135], v[140:143], v[62:65]
	v_mfma_f32_16x16x32_bf16 v[66:69], v[118:121], v[176:179], v[66:69]
	v_mfma_f32_16x16x32_bf16 v[70:73], v[132:135], v[176:179], v[70:73]
	v_mfma_f32_16x16x32_bf16 v[74:77], v[118:121], v[188:191], v[74:77]
	v_mfma_f32_16x16x32_bf16 v[78:81], v[132:135], v[188:191], v[78:81]
	v_mfma_f32_16x16x32_bf16 v[82:85], v[118:121], v[196:199], v[82:85]
	v_mfma_f32_16x16x32_bf16 v[86:89], v[122:125], v[192:195], v[90:93]
	v_mfma_f32_16x16x32_bf16 v[200:203], v[132:135], v[196:199], v[86:89]
	s_setprio 0
	s_barrier
	s_nop 4
	ds_read_b128 v[86:89], v144
	ds_read_b128 v[90:93], v144 offset:1024
	ds_read_b128 v[204:207], v144 offset:2048
	ds_read_b128 v[208:211], v144 offset:3072
	s_barrier
	s_waitcnt lgkmcnt(0)
	s_setprio 1
	s_waitcnt lgkmcnt(0)
	v_mfma_f32_16x16x32_bf16 v[30:33], v[204:207], v[136:139], v[30:33]
	v_mfma_f32_16x16x32_bf16 v[10:13], v[86:89], v[136:139], v[10:13]
	v_mfma_f32_16x16x32_bf16 v[136:139], v[208:211], v[140:143], v[30:33]
	v_mfma_f32_16x16x32_bf16 v[30:33], v[86:89], v[152:155], v[34:37]
	v_mfma_f32_16x16x32_bf16 v[10:13], v[90:93], v[140:143], v[10:13]
	v_mfma_f32_16x16x32_bf16 v[140:143], v[90:93], v[176:179], v[30:33]
	v_mfma_f32_16x16x32_bf16 v[30:33], v[204:207], v[152:155], v[38:41]
	v_mfma_f32_16x16x32_bf16 v[152:155], v[208:211], v[176:179], v[30:33]
	v_mfma_f32_16x16x32_bf16 v[30:33], v[86:89], v[184:187], v[42:45]
	v_mfma_f32_16x16x32_bf16 v[40:43], v[90:93], v[188:191], v[30:33]
	v_mfma_f32_16x16x32_bf16 v[30:33], v[204:207], v[184:187], v[46:49]
	v_mfma_f32_16x16x32_bf16 v[44:47], v[208:211], v[188:191], v[30:33]
	v_mfma_f32_16x16x32_bf16 v[30:33], v[86:89], v[192:195], v[50:53]
	v_mfma_f32_16x16x32_bf16 v[48:51], v[90:93], v[196:199], v[30:33]
	v_mfma_f32_16x16x32_bf16 v[30:33], v[204:207], v[192:195], v[54:57]
	v_mfma_f32_16x16x32_bf16 v[52:55], v[208:211], v[196:199], v[30:33]
	s_setprio 0
	s_barrier
	s_nop 4
	ds_read_b128 v[30:33], v183 offset:16384
	ds_read_b128 v[34:37], v183 offset:17408
	ds_read_b128 v[176:179], v183 offset:18432
	ds_read_b128 v[184:187], v183 offset:19456
	ds_read_b128 v[188:191], v183 offset:20480
	ds_read_b128 v[192:195], v183 offset:21504
	ds_read_b128 v[196:199], v183 offset:22528
	ds_read_b128 v[212:215], v183 offset:23552
	s_waitcnt vmcnt(4)
	s_barrier
	s_waitcnt lgkmcnt(0)
	s_setprio 1
	s_waitcnt lgkmcnt(0)
	v_mfma_f32_16x16x32_bf16 v[4:7], v[114:117], v[30:33], v[6:9]
	v_mfma_f32_16x16x32_bf16 v[14:17], v[114:117], v[196:199], v[14:17]
	v_mfma_f32_16x16x32_bf16 v[4:7], v[118:121], v[34:37], v[4:7]
	v_mfma_f32_16x16x32_bf16 v[156:159], v[122:125], v[30:33], v[156:159]
	v_mfma_f32_16x16x32_bf16 v[160:163], v[114:117], v[176:179], v[160:163]
	v_mfma_f32_16x16x32_bf16 v[164:167], v[122:125], v[176:179], v[164:167]
	v_mfma_f32_16x16x32_bf16 v[168:171], v[114:117], v[188:191], v[168:171]
	v_mfma_f32_16x16x32_bf16 v[172:175], v[122:125], v[188:191], v[172:175]
	v_mfma_f32_16x16x32_bf16 v[216:219], v[118:121], v[212:215], v[14:17]
	v_mfma_f32_16x16x32_bf16 v[14:17], v[122:125], v[196:199], v[18:21]
	v_mfma_f32_16x16x32_bf16 v[156:159], v[132:135], v[34:37], v[156:159]
	v_mfma_f32_16x16x32_bf16 v[160:163], v[118:121], v[184:187], v[160:163]
	v_mfma_f32_16x16x32_bf16 v[164:167], v[132:135], v[184:187], v[164:167]
	v_mfma_f32_16x16x32_bf16 v[168:171], v[118:121], v[192:195], v[168:171]
	v_mfma_f32_16x16x32_bf16 v[172:175], v[132:135], v[192:195], v[172:175]
	v_mfma_f32_16x16x32_bf16 v[132:135], v[132:135], v[212:215], v[14:17]
	s_setprio 0
	s_setprio 1
	v_mfma_f32_16x16x32_bf16 v[14:17], v[86:89], v[30:33], v[22:25]
	v_mfma_f32_16x16x32_bf16 v[220:223], v[90:93], v[34:37], v[14:17]
	v_mfma_f32_16x16x32_bf16 v[14:17], v[204:207], v[30:33], v[26:29]
	v_mfma_f32_16x16x32_bf16 v[24:27], v[208:211], v[34:37], v[14:17]
	v_mfma_f32_16x16x32_bf16 v[14:17], v[86:89], v[176:179], v[58:61]
	v_mfma_f32_16x16x32_bf16 v[28:31], v[90:93], v[184:187], v[14:17]
	v_mfma_f32_16x16x32_bf16 v[14:17], v[204:207], v[176:179], v[102:105]
	v_mfma_f32_16x16x32_bf16 v[176:179], v[208:211], v[184:187], v[14:17]
	v_mfma_f32_16x16x32_bf16 v[14:17], v[86:89], v[188:191], v[106:109]
	v_mfma_f32_16x16x32_bf16 v[184:187], v[90:93], v[192:195], v[14:17]
	v_mfma_f32_16x16x32_bf16 v[14:17], v[204:207], v[188:191], v[110:113]
	v_mfma_f32_16x16x32_bf16 v[188:191], v[208:211], v[192:195], v[14:17]
	v_mfma_f32_16x16x32_bf16 v[14:17], v[86:89], v[196:199], v[94:97]
	v_mfma_f32_16x16x32_bf16 v[192:195], v[90:93], v[212:215], v[14:17]
	v_mfma_f32_16x16x32_bf16 v[14:17], v[204:207], v[196:199], v[98:101]
	v_mfma_f32_16x16x32_bf16 v[196:199], v[208:211], v[212:215], v[14:17]
	s_setprio 0
	s_barrier
	ds_read_b128 v[204:207], v145
	ds_read_b128 v[208:211], v145 offset:1024
	ds_read_b128 v[212:215], v145 offset:2048
	ds_read_b128 v[224:227], v145 offset:3072
	s_nop 0
	ds_read_b128 v[14:17], v183 offset:32768
	ds_read_b128 v[18:21], v183 offset:33792
	ds_read_b128 v[96:99], v183 offset:34816
	ds_read_b128 v[100:103], v183 offset:35840
	ds_read_b128 v[228:231], v183 offset:36864
	ds_read_b128 v[232:235], v183 offset:37888
	ds_read_b128 v[236:239], v183 offset:38912
	ds_read_b128 v[240:243], v183 offset:39936
	s_waitcnt vmcnt(2)
	s_barrier
	s_waitcnt lgkmcnt(0)
	s_setprio 1
	s_waitcnt lgkmcnt(0)
	v_mfma_f32_16x16x32_bf16 v[0:3], v[204:207], v[14:17], v[0:3]
	v_mfma_f32_16x16x32_bf16 v[104:107], v[208:211], v[18:21], v[0:3]
	v_mfma_f32_16x16x32_bf16 v[0:3], v[212:215], v[14:17], v[62:65]
	v_mfma_f32_16x16x32_bf16 v[108:111], v[224:227], v[18:21], v[0:3]
	v_mfma_f32_16x16x32_bf16 v[0:3], v[204:207], v[96:99], v[66:69]
	v_mfma_f32_16x16x32_bf16 v[88:91], v[208:211], v[100:103], v[0:3]
	v_mfma_f32_16x16x32_bf16 v[0:3], v[212:215], v[96:99], v[70:73]
	v_mfma_f32_16x16x32_bf16 v[92:95], v[224:227], v[100:103], v[0:3]
	v_mfma_f32_16x16x32_bf16 v[0:3], v[204:207], v[228:231], v[74:77]
	v_mfma_f32_16x16x32_bf16 v[56:59], v[208:211], v[232:235], v[0:3]
	v_mfma_f32_16x16x32_bf16 v[0:3], v[212:215], v[228:231], v[78:81]
	v_mfma_f32_16x16x32_bf16 v[60:63], v[224:227], v[232:235], v[0:3]
	v_mfma_f32_16x16x32_bf16 v[0:3], v[204:207], v[236:239], v[82:85]
	v_mfma_f32_16x16x32_bf16 v[32:35], v[208:211], v[240:243], v[0:3]
	v_mfma_f32_16x16x32_bf16 v[0:3], v[212:215], v[236:239], v[200:203]
	v_mfma_f32_16x16x32_bf16 v[36:39], v[224:227], v[240:243], v[0:3]
	s_setprio 0
	s_barrier
	ds_read_b128 v[200:203], v146
	ds_read_b128 v[244:247], v146 offset:1024
	ds_read_b128 v[248:251], v146 offset:2048
	ds_read_b128 v[144:147], v146 offset:3072
	s_waitcnt vmcnt(0)
	s_barrier
	s_waitcnt lgkmcnt(0)
	s_setprio 1
	s_waitcnt lgkmcnt(0)
	v_mfma_f32_16x16x32_bf16 v[0:3], v[200:203], v[14:17], v[10:13]
	v_mfma_f32_16x16x32_bf16 v[120:123], v[244:247], v[18:21], v[0:3]
	v_mfma_f32_16x16x32_bf16 v[0:3], v[248:251], v[14:17], v[136:139]
	v_mfma_f32_16x16x32_bf16 v[124:127], v[144:147], v[18:21], v[0:3]
	v_mfma_f32_16x16x32_bf16 v[0:3], v[200:203], v[96:99], v[140:143]
	v_mfma_f32_16x16x32_bf16 v[112:115], v[244:247], v[100:103], v[0:3]
	v_mfma_f32_16x16x32_bf16 v[0:3], v[248:251], v[96:99], v[152:155]
	v_mfma_f32_16x16x32_bf16 v[116:119], v[144:147], v[100:103], v[0:3]
	v_mfma_f32_16x16x32_bf16 v[0:3], v[200:203], v[228:231], v[40:43]
	v_mfma_f32_16x16x32_bf16 v[96:99], v[244:247], v[232:235], v[0:3]
	v_mfma_f32_16x16x32_bf16 v[0:3], v[248:251], v[228:231], v[44:47]
	v_mfma_f32_16x16x32_bf16 v[100:103], v[144:147], v[232:235], v[0:3]
	v_mfma_f32_16x16x32_bf16 v[0:3], v[200:203], v[236:239], v[48:51]
	v_mfma_f32_16x16x32_bf16 v[64:67], v[244:247], v[240:243], v[0:3]
	v_mfma_f32_16x16x32_bf16 v[0:3], v[248:251], v[236:239], v[52:55]
	v_mfma_f32_16x16x32_bf16 v[68:71], v[144:147], v[240:243], v[0:3]
	s_setprio 0
	s_barrier
	ds_read_b128 v[8:11], v183 offset:49152
	ds_read_b128 v[12:15], v183 offset:50176
	ds_read_b128 v[52:55], v183 offset:51200
	ds_read_b128 v[136:139], v183 offset:52224
	ds_read_b128 v[140:143], v183 offset:53248
	ds_read_b128 v[152:155], v183 offset:54272
	ds_read_b128 v[228:231], v183 offset:55296
	ds_read_b128 v[232:235], v183 offset:56320
	s_barrier
	s_waitcnt lgkmcnt(0)
	s_setprio 1
	s_waitcnt lgkmcnt(0)
	v_mfma_f32_16x16x32_bf16 v[0:3], v[204:207], v[8:11], v[4:7]
	v_mfma_f32_16x16x32_bf16 v[72:75], v[208:211], v[12:15], v[0:3]
	v_mfma_f32_16x16x32_bf16 v[0:3], v[212:215], v[8:11], v[156:159]
	v_mfma_f32_16x16x32_bf16 v[76:79], v[224:227], v[12:15], v[0:3]
	v_mfma_f32_16x16x32_bf16 v[0:3], v[204:207], v[52:55], v[160:163]
	v_mfma_f32_16x16x32_bf16 v[40:43], v[208:211], v[136:139], v[0:3]
	v_mfma_f32_16x16x32_bf16 v[0:3], v[212:215], v[52:55], v[164:167]
	v_mfma_f32_16x16x32_bf16 v[44:47], v[224:227], v[136:139], v[0:3]
	v_mfma_f32_16x16x32_bf16 v[0:3], v[204:207], v[140:143], v[168:171]
	v_mfma_f32_16x16x32_bf16 v[16:19], v[208:211], v[152:155], v[0:3]
	v_mfma_f32_16x16x32_bf16 v[0:3], v[212:215], v[140:143], v[172:175]
	v_mfma_f32_16x16x32_bf16 v[20:23], v[224:227], v[152:155], v[0:3]
	v_mfma_f32_16x16x32_bf16 v[0:3], v[204:207], v[228:231], v[216:219]
	v_mfma_f32_16x16x32_bf16 v[4:7], v[212:215], v[228:231], v[132:135]
	v_mfma_f32_16x16x32_bf16 v[0:3], v[208:211], v[232:235], v[0:3]
	v_mfma_f32_16x16x32_bf16 v[4:7], v[224:227], v[232:235], v[4:7]
	s_setprio 0
	s_setprio 1
	v_mfma_f32_16x16x32_bf16 v[48:51], v[200:203], v[8:11], v[220:223]
	v_mfma_f32_16x16x32_bf16 v[8:11], v[248:251], v[8:11], v[24:27]
	v_mfma_f32_16x16x32_bf16 v[84:87], v[144:147], v[12:15], v[8:11]
	v_mfma_f32_16x16x32_bf16 v[8:11], v[200:203], v[52:55], v[28:31]
	v_mfma_f32_16x16x32_bf16 v[80:83], v[244:247], v[12:15], v[48:51]
	v_mfma_f32_16x16x32_bf16 v[48:51], v[244:247], v[136:139], v[8:11]
	v_mfma_f32_16x16x32_bf16 v[8:11], v[248:251], v[52:55], v[176:179]
	v_mfma_f32_16x16x32_bf16 v[52:55], v[144:147], v[136:139], v[8:11]
	v_mfma_f32_16x16x32_bf16 v[8:11], v[200:203], v[140:143], v[184:187]
	v_mfma_f32_16x16x32_bf16 v[24:27], v[244:247], v[152:155], v[8:11]
	v_mfma_f32_16x16x32_bf16 v[8:11], v[248:251], v[140:143], v[188:191]
	v_mfma_f32_16x16x32_bf16 v[28:31], v[144:147], v[152:155], v[8:11]
	v_mfma_f32_16x16x32_bf16 v[8:11], v[200:203], v[228:231], v[192:195]
	v_mfma_f32_16x16x32_bf16 v[12:15], v[248:251], v[228:231], v[196:199]
	v_mfma_f32_16x16x32_bf16 v[8:11], v[244:247], v[232:235], v[8:11]
	v_mfma_f32_16x16x32_bf16 v[12:15], v[144:147], v[232:235], v[12:15]
	s_setprio 0
	s_cmpk_gt_u32 s0, 0xff
	s_barrier
	s_cbranch_scc1 .LBB0_261
	s_barrier
	s_branch .LBB0_261

.LBB0_407:
	v_readfirstlane_b32 s99, v182
	s_nop 3
	s_lshr_b32 s99, s99, 8
	s_ashr_i32 s4, s51, 8
	s_and_b32 s0, s51, 0xff
	s_cmp_eq_u32 s4, 1
	s_cselect_b32 s3, 4, 16
	s_cselect_b32 s6, 2, 4
	s_cmpk_lt_u32 s51, 0x100
	s_cselect_b32 s48, 0, s6
	s_cselect_b32 s5, 1, s3
	s_lshr_b32 s3, 16, s48
	s_add_i32 s3, s3, -1
	s_sub_i32 s6, 4, s48
	s_and_b32 s3, s3, s0
	s_lshr_b32 s0, s0, s6
	s_add_i32 s6, s5, -1
	s_and_b32 s49, s0, s6
	s_bfe_u32 s0, s51, 0x10007
	s_bfe_u32 s28, s51, 0x30004
	s_mul_i32 s6, s0, 0x3000000
	v_readlane_b32 s7, v252, 33
	s_add_u32 s6, s7, s6
	v_readlane_b32 s7, v252, 34
	s_addc_u32 s7, s7, 0
	s_lshl_b32 s8, s28, 8
	v_mov_b32_e32 v36, v182
	s_add_u32 s6, s6, s8
	s_addc_u32 s7, s7, 0
	v_and_b32_e32 v34, 15, v36
	v_readfirstlane_b32 s1, v36
	v_ashrrev_i32_e32 v35, 4, v36
	s_cmp_lg_u32 s3, 0
	v_lshlrev_b32_e32 v72, 3, v34
	v_lshlrev_b32_e32 v32, 4, v34
	s_waitcnt vmcnt(0) lgkmcnt(0)
	s_barrier
	s_cbranch_scc0 .LBB0_418
	s_lshl_b32 s52, s3, 9
	v_add_u32_e32 v26, s52, v35
	v_add_u32_e32 v0, 0xffffff80, v26
	v_mov_b32_e32 v33, v73
	v_lshlrev_b32_e32 v0, s48, v0
	v_lshl_add_u64 v[24:25], s[6:7], 0, v[32:33]
	v_add_u32_e32 v0, s49, v0
	v_add_u32_e32 v8, 0xffffffa0, v26
	v_mad_i64_i32 v[0:1], s[8:9], v0, s88, v[24:25]
	v_lshlrev_b32_e32 v8, s48, v8
	v_add_co_u32_e32 v2, vcc, 0x1000, v0
	v_add_u32_e32 v8, s49, v8
	v_subrev_u32_e32 v16, 64, v26
	v_addc_co_u32_e32 v3, vcc, 0, v1, vcc
	v_mad_i64_i32 v[8:9], s[8:9], v8, s88, v[24:25]
	v_lshlrev_b32_e32 v16, s48, v16
	v_add_co_u32_e32 v12, vcc, 0x1000, v8
	v_add_u32_e32 v16, s49, v16
	v_subrev_u32_e32 v26, 32, v26
	v_addc_co_u32_e32 v13, vcc, 0, v9, vcc
	v_mad_i64_i32 v[16:17], s[8:9], v16, s88, v[24:25]
	v_lshlrev_b32_e32 v26, s48, v26
	v_add_co_u32_e32 v20, vcc, 0x1000, v16
	v_add_u32_e32 v26, s49, v26
	s_nop 0
	v_addc_co_u32_e32 v21, vcc, 0, v17, vcc
	v_mad_i64_i32 v[24:25], s[8:9], v26, s88, v[24:25]
	v_add_co_u32_e32 v28, vcc, 0x1000, v24
	global_load_dwordx4 v[4:7], v[0:1], off offset:2048
	s_nop 0
	global_load_dwordx4 v[0:3], v[2:3], off
	v_addc_co_u32_e32 v29, vcc, 0, v25, vcc
	global_load_dwordx4 v[8:11], v[8:9], off offset:2048
	s_nop 0
	global_load_dwordx4 v[12:15], v[12:13], off
	s_nop 0
	global_load_dwordx4 v[16:19], v[16:17], off offset:2048
	s_nop 0
	global_load_dwordx4 v[20:23], v[20:21], off
	s_nop 0
	global_load_dwordx4 v[24:27], v[24:25], off offset:2048
	s_nop 0
	global_load_dwordx4 v[28:31], v[28:29], off
	s_lshl_b32 s29, s28, 7
	s_cbranch_execnz .LBB0_410

.LBB0_410:
	v_add_u32_e32 v33, s52, v35
	v_lshlrev_b32_e32 v37, s48, v33
	v_lshl_add_u64 v[74:75], v[72:73], 1, s[6:7]
	v_add_u32_e32 v37, s49, v37
	v_mad_i64_i32 v[38:39], s[8:9], v37, s88, v[74:75]
	v_add_lshl_u32 v37, v33, 32, s48
	v_add_co_u32_e32 v42, vcc, s89, v38
	v_add_u32_e32 v37, s49, v37
	s_nop 0
	v_addc_co_u32_e32 v43, vcc, 0, v39, vcc
	v_mad_i64_i32 v[46:47], s[8:9], v37, s88, v[74:75]
	v_add_lshl_u32 v37, v33, 64, s48
	v_add_co_u32_e32 v48, vcc, s89, v46
	v_add_u32_e32 v37, s49, v37
	v_add_u32_e32 v33, 0x60, v33
	global_load_dwordx4 v[38:41], v[38:39], off offset:2048
	s_nop 0
	global_load_dwordx4 v[42:45], v[42:43], off
	v_addc_co_u32_e32 v49, vcc, 0, v47, vcc
	global_load_dwordx4 v[64:67], v[46:47], off offset:2048
	global_load_dwordx4 v[68:71], v[48:49], off
	v_mad_i64_i32 v[46:47], s[8:9], v37, s88, v[74:75]
	v_lshlrev_b32_e32 v33, s48, v33
	v_add_co_u32_e32 v48, vcc, s89, v46
	v_add_u32_e32 v33, s49, v33
	s_nop 0
	v_addc_co_u32_e32 v49, vcc, 0, v47, vcc
	global_load_dwordx4 v[76:79], v[46:47], off offset:2048
	global_load_dwordx4 v[84:87], v[48:49], off
	v_mad_i64_i32 v[46:47], s[8:9], v33, s88, v[74:75]
	v_add_co_u32_e32 v48, vcc, s89, v46
	s_ashr_i32 s10, s1, 2
	s_nop 0
	v_addc_co_u32_e32 v49, vcc, 0, v47, vcc
	global_load_dwordx4 v[88:91], v[46:47], off offset:2048
	global_load_dwordx4 v[92:95], v[48:49], off
	s_movk_i32 s8, 0x110
	v_mul_lo_u32 v33, v35, s8
	s_and_b32 s30, s10, -16
	v_add3_u32 v83, 0, v32, v33
	v_add3_u32 v98, s90, v32, v33
	v_add3_u32 v99, s91, v32, v33
	v_or_b32_e32 v32, s30, v34
	v_add_u32_e32 v32, s52, v32
	v_lshlrev_b32_e32 v32, s48, v32
	v_bfe_u32 v37, v36, 4, 2
	v_mov_b64_e32 v[46:47], s[6:7]
	s_add_i32 s8, s28, 1
	v_add_u32_e32 v32, s49, v32
	v_mov_b32_e32 v97, v73
	v_lshlrev_b32_e32 v96, 4, v37
	v_cvt_f32_ubyte0_e32 v100, s8
	v_mad_i64_i32 v[32:33], s[8:9], v32, s88, v[46:47]
	s_waitcnt vmcnt(15)
	ds_write_b128 v83, v[4:7]
	s_waitcnt vmcnt(14)
	ds_write_b128 v83, v[0:3] offset:34816
	s_waitcnt vmcnt(13)
	ds_write_b128 v83, v[8:11] offset:8704
	s_waitcnt vmcnt(12)
	ds_write_b128 v83, v[12:15] offset:43520
	s_waitcnt vmcnt(11)
	ds_write_b128 v83, v[16:19] offset:17408
	s_waitcnt vmcnt(10)
	ds_write_b128 v83, v[20:23] offset:52224
	s_waitcnt vmcnt(9)
	ds_write_b128 v83, v[24:27] offset:26112
	s_waitcnt vmcnt(8)
	ds_write_b128 v83, v[28:31] offset:60928
	v_lshl_add_u64 v[32:33], v[32:33], 0, v[96:97]
	global_load_dwordx4 v[48:51], v[32:33], off
	global_load_dwordx4 v[52:55], v[32:33], off offset:64
	global_load_dwordx4 v[56:59], v[32:33], off offset:128
	global_load_dwordx4 v[60:63], v[32:33], off offset:192
	s_mov_b32 s8, 0x42fc0000
	v_cmp_lt_f32_e32 vcc, s8, v100
	s_and_b64 s[8:9], vcc, exec
	s_cselect_b32 s8, 0xffffffc0, 0
	v_cvt_f32_ubyte0_e32 v33, s5
	s_ashr_i32 s5, s4, 31
	s_lshl_b32 s0, s0, 13
	s_ashr_i32 s22, s1, 7
	s_lshl_b64 s[44:45], s[4:5], 14
	s_or_b32 s96, s49, s0
	s_cmp_lt_i32 s22, 4
	s_cselect_b64 s[64:65], -1, 0
	s_and_b32 s1, s22, 3
	s_add_i32 s0, s22, 1
	s_cmp_lt_i32 s22, 3
	s_cselect_b64 s[66:67], -1, 0
	s_and_b32 s0, s0, 3
	v_cndmask_b32_e32 v32, 0, v80, vcc
	s_cmp_lt_i32 s22, 2
	v_sub_f32_e32 v32, v32, v100
	s_mul_i32 s97, s1, 0x2200
	s_cselect_b64 s[68:69], -1, 0
	s_xor_b32 s1, s1, 2
	v_exp_f32_e32 v32, v32
	v_and_b32_e32 v36, 3, v36
	v_lshlrev_b32_e32 v72, 3, v37
	v_cmp_eq_u32_e64 s[4:5], 0, v37
	v_ldexp_f32 v32, v32, s8
	v_mul_f32_e32 v32, v32, v33
	v_lshrrev_b32_e32 v33, 2, v34
	s_waitcnt vmcnt(11)
	ds_write_b128 v98, v[38:41]
	s_waitcnt vmcnt(9)
	ds_write_b128 v98, v[64:67] offset:8704
	s_waitcnt vmcnt(7)
	ds_write_b128 v98, v[76:79] offset:17408
	ds_write_b128 v99, v[42:45]
	ds_write_b128 v99, v[68:71] offset:8704
	s_waitcnt vmcnt(6)
	ds_write_b128 v99, v[84:87] offset:17408
	s_waitcnt vmcnt(5)
	ds_write_b128 v98, v[88:91] offset:26112
	s_waitcnt vmcnt(4)
	ds_write_b128 v99, v[92:95] offset:26112
	v_lshl_add_u64 v[76:77], s[6:7], 0, v[96:97]
	s_add_i32 s6, s22, -1
	s_cmp_lt_i32 s22, 1
	s_cselect_b64 s[70:71], -1, 0
	s_and_b32 s93, s6, 3
	s_cmp_lt_i32 s22, 0
	s_cselect_b64 s[72:73], -1, 0
	s_cmp_gt_i32 s22, 3
	s_cselect_b64 s[74:75], -1, 0
	s_cmp_gt_i32 s22, 2
	s_cselect_b64 s[76:77], -1, 0
	s_cmp_gt_i32 s22, 1
	v_lshl_or_b32 v38, v33, 3, v36
	v_and_b32_e32 v40, 64, v81
	s_cselect_b64 s[78:79], -1, 0
	s_cmp_gt_i32 s22, 0
	v_mul_u32_u24_e32 v38, 0x110, v38
	v_xor_b32_e32 v39, 16, v81
	v_add_u32_e32 v40, 64, v40
	s_cselect_b64 s[80:81], -1, 0
	s_cmp_gt_i32 s22, -1
	v_add3_u32 v84, 0, v38, v96
	v_and_or_b32 v38, s10, 16, v34
	v_cmp_lt_i32_e32 vcc, v39, v40
	s_cselect_b64 s[82:83], -1, 0
	s_lshl_b32 s29, s29, 1
	v_or_b32_e32 v38, 0x80, v38
	v_cndmask_b32_e32 v39, v81, v39, vcc
	s_add_u32 s34, s56, s29
	v_sub_u32_e32 v64, v38, v72
	v_lshlrev_b32_e32 v86, 2, v39
	v_xor_b32_e32 v39, 32, v81
	s_addc_u32 s35, s57, 0
	s_lshl_b32 s28, s28, 2
	v_mul_f32_e32 v32, 0x3fb8aa3b, v32
	v_cvt_f32_ubyte0_e32 v38, v64
	v_cmp_lt_i32_e32 vcc, v39, v40
	v_or_b32_e32 v33, v72, v33
	s_add_u32 s84, s50, s28
	v_mul_f32_e64 v85, -v32, v38
	v_cndmask_b32_e32 v39, v81, v39, vcc
	v_mul_u32_u24_e32 v33, 0x110, v33
	v_lshlrev_b32_e32 v36, 3, v36
	s_addc_u32 s85, s2, 0
	s_add_i32 s28, s52, s30
	v_lshlrev_b32_e32 v87, 2, v39
	v_add3_u32 v88, v36, s92, v33
	v_fma_f32 v89, 0, v32, v85
	s_movk_i32 s26, 0x81
	v_fma_f32 v90, -v32, v38, v32
	s_movk_i32 s31, 0x82
	v_fma_f32 v91, 2.0, v32, v85
	s_movk_i32 s33, 0x83
	v_fmamk_f32 v92, v32, 0x40400000, v85
	s_movk_i32 s36, 0x84
	v_fma_f32 v93, 4.0, v32, v85
	s_movk_i32 s37, 0x85
	v_fmamk_f32 v94, v32, 0x40a00000, v85
	s_movk_i32 s38, 0x86
	v_fmamk_f32 v95, v32, 0x40c00000, v85
	s_movk_i32 s18, 0x87
	v_fmamk_f32 v96, v32, 0x40e00000, v85
	s_movk_i32 s20, 0x88
	v_fmamk_f32 v97, v32, 0x42000000, v85
	v_fmamk_f32 v98, v32, 0x42040000, v85
	v_fmamk_f32 v99, v32, 0x42080000, v85
	v_fmamk_f32 v100, v32, 0x420c0000, v85
	v_fmamk_f32 v101, v32, 0x42100000, v85
	v_fmamk_f32 v102, v32, 0x42140000, v85
	v_fmamk_f32 v103, v32, 0x42180000, v85
	v_fmamk_f32 v104, v32, 0x421c0000, v85
	v_fmamk_f32 v105, v32, 0x42800000, v85
	v_fmamk_f32 v106, v32, 0x42820000, v85
	v_fmamk_f32 v107, v32, 0x42840000, v85
	v_fmamk_f32 v108, v32, 0x42860000, v85
	v_fmamk_f32 v109, v32, 0x42880000, v85
	v_fmamk_f32 v110, v32, 0x428a0000, v85
	v_fmamk_f32 v111, v32, 0x428c0000, v85
	v_fmamk_f32 v112, v32, 0x428e0000, v85
	v_fmamk_f32 v113, v32, 0x42c00000, v85
	v_fmamk_f32 v114, v32, 0x42c20000, v85
	v_fmamk_f32 v115, v32, 0x42c40000, v85
	v_fmamk_f32 v116, v32, 0x42c60000, v85
	v_fmamk_f32 v117, v32, 0x42c80000, v85
	v_fmamk_f32 v118, v32, 0x42ca0000, v85
	v_fmamk_f32 v119, v32, 0x42cc0000, v85
	v_fmamk_f32 v120, v32, 0x42ce0000, v85
	v_fmamk_f32 v121, v32, 0x43000000, v85
	s_movk_i32 s22, 0x7f
	v_fmamk_f32 v122, v32, 0x43010000, v85
	s_movk_i32 s24, 0x80
	v_fmamk_f32 v123, v32, 0x43020000, v85
	v_fmamk_f32 v124, v32, 0x43030000, v85
	v_lshl_add_u64 v[78:79], s[34:35], 0, v[72:73]
	v_add_u32_e32 v72, s28, v34
	v_fmamk_f32 v125, v32, 0x43040000, v85
	v_fmamk_f32 v126, v32, 0x43050000, v85
	v_fmamk_f32 v127, v32, 0x43060000, v85
	v_fmac_f32_e32 v85, 0x43070000, v32
	v_add_u32_e32 v128, s52, v35
	s_waitcnt vmcnt(3)
	v_mov_b64_e32 v[32:33], v[48:49]
	s_waitcnt vmcnt(2)
	v_mov_b64_e32 v[36:37], v[52:53]
	s_waitcnt vmcnt(1)
	v_mov_b64_e32 v[40:41], v[56:57]
	s_waitcnt vmcnt(0)
	v_mov_b64_e32 v[44:45], v[60:61]
	s_mov_b32 s53, 1
	s_mov_b32 s3, 0
	s_mulk_i32 s0, 0x2200
	s_mulk_i32 s1, 0x2200
	s_mulk_i32 s93, 0x2200
	v_cmp_gt_u32_e64 s[6:7], s26, v64
	v_cmp_gt_u32_e64 s[8:9], s31, v64
	v_cmp_gt_u32_e64 s[10:11], s33, v64
	v_cmp_gt_u32_e64 s[12:13], s36, v64
	v_cmp_gt_u32_e64 s[14:15], s37, v64
	v_cmp_gt_u32_e64 s[16:17], s38, v64
	v_cmp_gt_u32_e64 s[18:19], s18, v64
	v_cmp_gt_u32_e64 s[20:21], s20, v64
	v_cmp_lt_u32_e64 s[22:23], s22, v64
	v_cmp_lt_u32_e64 s[24:25], s24, v64
	v_cmp_lt_u32_e64 s[26:27], s26, v64
	v_cmp_lt_u32_e64 s[28:29], s31, v64
	v_mov_b64_e32 v[34:35], v[50:51]
	v_mov_b64_e32 v[38:39], v[54:55]
	v_mov_b64_e32 v[42:43], v[58:59]
	v_mov_b64_e32 v[46:47], v[62:63]
	v_cmp_lt_u32_e64 s[30:31], s33, v64
	v_cmp_lt_u32_e64 s[34:35], s36, v64
	v_cmp_lt_u32_e64 s[36:37], s37, v64
	v_cmp_lt_u32_e64 s[38:39], s38, v64
	s_waitcnt lgkmcnt(0)
	s_barrier
	s_branch .LBB0_412
	s_nop 0
	s_nop 0
	s_nop 0
	s_nop 0
	s_nop 0
	s_nop 0
	s_nop 0
	s_nop 0
	s_nop 0
	s_nop 0
	s_nop 0
	s_nop 0
	s_nop 0
	s_nop 0
	s_nop 0
	s_nop 0
	s_nop 0
	s_nop 0
	s_nop 0
	s_nop 0
	s_nop 0
	s_nop 0
	s_nop 0
	s_nop 0
	s_nop 0
	s_nop 0
	s_nop 0
	s_nop 0
	s_nop 0
	s_nop 0
	s_nop 0
	s_nop 0
	s_nop 0
	s_nop 0
	s_nop 0
	s_nop 0
	s_nop 0
	s_nop 0
	s_nop 0
	s_nop 0
	s_nop 0
	s_nop 0
	s_nop 0
	s_nop 0
	s_nop 0
	s_nop 0
	s_nop 0
	s_nop 0
	s_nop 0
	s_nop 0
	s_nop 0
	s_nop 0
	s_nop 0
	s_nop 0
	s_nop 0
	s_nop 0
	s_nop 0
	s_nop 0
	s_nop 0
	s_nop 0
	s_nop 0

.Lstg_p0_b:
	s_add_i32 s40, s53, -1
	s_add_i32 s42, s52, s3
	s_and_b32 s94, s40, 1
	s_and_b32 s43, s53, 1
	s_and_b64 s[40:41], s[64:65], exec
	s_cselect_b32 s40, s94, s43
	s_mul_i32 s63, s40, 0x11000
	s_add_i32 s63, s63, s97
	s_and_b64 s[40:41], s[66:67], exec
	s_cselect_b32 s40, s94, s43
	s_mul_i32 s62, s40, 0x11000
	s_add_i32 s62, s62, s0
	s_and_b64 s[40:41], s[68:69], exec
	v_add_u32_e32 v150, s63, v84
	v_add_u32_e32 v178, s62, v84
	v_lshlrev_b32_e32 v129, s48, v64
	s_cselect_b32 s40, s94, s43
	ds_read_b128 v[64:67], v150
	ds_read_b128 v[68:71], v150 offset:64
	ds_read_b128 v[130:133], v150 offset:128
	ds_read_b128 v[134:137], v150 offset:192
	ds_read_b128 v[138:141], v150 offset:1088
	ds_read_b128 v[142:145], v150 offset:1152
	ds_read_b128 v[146:149], v150 offset:1216
	ds_read_b128 v[150:153], v150 offset:1280
	ds_read_b128 v[154:157], v178
	ds_read_b128 v[158:161], v178 offset:64
	ds_read_b128 v[162:165], v178 offset:128
	ds_read_b128 v[166:169], v178 offset:192
	ds_read_b128 v[170:173], v178 offset:1088
	ds_read_b128 v[174:177], v178 offset:1152
	ds_read_b128 v[184:187], v178 offset:1216
	ds_read_b128 v[188:191], v178 offset:1280
	s_mul_i32 s95, s40, 0x11000
	s_add_i32 s95, s95, s1
	s_and_b64 s[40:41], s[70:71], exec
	s_cselect_b32 s40, s94, s43
	s_mul_i32 s41, s40, 0x11000
	s_add_i32 s41, s41, s93
	s_and_b64 s[60:61], s[72:73], exec
	s_cselect_b32 s40, s94, s43
	s_mul_i32 s40, s40, 0x11000
	s_add_i32 s40, s40, s97
	s_waitcnt lgkmcnt(14)
	v_mfma_f32_16x16x32_bf16 v[64:67], v[64:67], v[48:51], 0
	v_mfma_f32_16x16x32_bf16 v[64:67], v[68:71], v[52:55], v[64:67]
	s_waitcnt lgkmcnt(11)
	v_mfma_f32_16x16x32_bf16 v[68:71], v[138:141], v[48:51], 0
	s_waitcnt lgkmcnt(10)
	v_mfma_f32_16x16x32_bf16 v[68:71], v[142:145], v[52:55], v[68:71]
	v_mfma_f32_16x16x32_bf16 v[64:67], v[130:133], v[56:59], v[64:67]
	s_waitcnt lgkmcnt(9)
	v_mfma_f32_16x16x32_bf16 v[68:71], v[146:149], v[56:59], v[68:71]
	v_mfma_f32_16x16x32_bf16 v[64:67], v[134:137], v[60:63], v[64:67]
	s_waitcnt lgkmcnt(8)
	v_mfma_f32_16x16x32_bf16 v[68:71], v[150:153], v[60:63], v[68:71]
	v_add_u32_e32 v178, s95, v84
	ds_read_b128 v[130:133], v178
	ds_read_b128 v[134:137], v178 offset:64
	ds_read_b128 v[138:141], v178 offset:128
	ds_read_b128 v[142:145], v178 offset:192
	ds_read_b128 v[146:149], v178 offset:1088
	ds_read_b128 v[150:153], v178 offset:1152
	ds_read_b128 v[192:195], v178 offset:1216
	ds_read_b128 v[196:199], v178 offset:1280
	s_waitcnt lgkmcnt(14)
	v_mfma_f32_16x16x32_bf16 v[154:157], v[154:157], v[48:51], 0
	v_mfma_f32_16x16x32_bf16 v[154:157], v[158:161], v[52:55], v[154:157]
	s_waitcnt lgkmcnt(11)
	v_mfma_f32_16x16x32_bf16 v[158:161], v[170:173], v[48:51], 0
	s_waitcnt lgkmcnt(10)
	v_mfma_f32_16x16x32_bf16 v[158:161], v[174:177], v[52:55], v[158:161]
	v_mfma_f32_16x16x32_bf16 v[154:157], v[162:165], v[56:59], v[154:157]
	s_waitcnt lgkmcnt(9)
	v_mfma_f32_16x16x32_bf16 v[158:161], v[184:187], v[56:59], v[158:161]
	v_mfma_f32_16x16x32_bf16 v[154:157], v[166:169], v[60:63], v[154:157]
	s_waitcnt lgkmcnt(8)
	v_mfma_f32_16x16x32_bf16 v[158:161], v[188:191], v[60:63], v[158:161]
	v_add_u32_e32 v178, s41, v84
	ds_read_b128 v[162:165], v178
	ds_read_b128 v[166:169], v178 offset:64
	ds_read_b128 v[170:173], v178 offset:128
	ds_read_b128 v[174:177], v178 offset:192
	ds_read_b128 v[184:187], v178 offset:1088
	ds_read_b128 v[188:191], v178 offset:1152
	ds_read_b128 v[200:203], v178 offset:1216
	ds_read_b128 v[204:207], v178 offset:1280
	s_waitcnt lgkmcnt(14)
	v_mfma_f32_16x16x32_bf16 v[130:133], v[130:133], v[48:51], 0
	v_mfma_f32_16x16x32_bf16 v[130:133], v[134:137], v[52:55], v[130:133]
	s_waitcnt lgkmcnt(11)
	v_mfma_f32_16x16x32_bf16 v[134:137], v[146:149], v[48:51], 0
	v_mfma_f32_16x16x32_bf16 v[130:133], v[138:141], v[56:59], v[130:133]
	s_waitcnt lgkmcnt(10)
	v_mfma_f32_16x16x32_bf16 v[134:137], v[150:153], v[52:55], v[134:137]
	v_mfma_f32_16x16x32_bf16 v[130:133], v[142:145], v[60:63], v[130:133]
	s_waitcnt lgkmcnt(9)
	v_mfma_f32_16x16x32_bf16 v[134:137], v[192:195], v[56:59], v[134:137]
	s_waitcnt lgkmcnt(8)
	v_mfma_f32_16x16x32_bf16 v[134:137], v[196:199], v[60:63], v[134:137]
	v_add_u32_e32 v178, s40, v84
	ds_read_b128 v[138:141], v178
	ds_read_b128 v[142:145], v178 offset:64
	ds_read_b128 v[146:149], v178 offset:128
	ds_read_b128 v[150:153], v178 offset:192
	ds_read_b128 v[192:195], v178 offset:1088
	ds_read_b128 v[196:199], v178 offset:1152
	ds_read_b128 v[208:211], v178 offset:1216
	ds_read_b128 v[212:215], v178 offset:1280
	s_waitcnt lgkmcnt(14)
	v_mfma_f32_16x16x32_bf16 v[162:165], v[162:165], v[48:51], 0
	v_mfma_f32_16x16x32_bf16 v[162:165], v[166:169], v[52:55], v[162:165]
	s_waitcnt lgkmcnt(11)
	v_mfma_f32_16x16x32_bf16 v[166:169], v[184:187], v[48:51], 0
	s_waitcnt lgkmcnt(10)
	v_mfma_f32_16x16x32_bf16 v[166:169], v[188:191], v[52:55], v[166:169]
	v_mfma_f32_16x16x32_bf16 v[162:165], v[170:173], v[56:59], v[162:165]
	s_waitcnt lgkmcnt(9)
	v_mfma_f32_16x16x32_bf16 v[166:169], v[200:203], v[56:59], v[166:169]
	v_mfma_f32_16x16x32_bf16 v[162:165], v[174:177], v[60:63], v[162:165]
	s_waitcnt lgkmcnt(8)
	v_mfma_f32_16x16x32_bf16 v[166:169], v[204:207], v[60:63], v[166:169]
	s_waitcnt lgkmcnt(7)
	v_mfma_f32_16x16x32_bf16 v[138:141], v[138:141], v[48:51], 0
	s_waitcnt lgkmcnt(3)
	v_mfma_f32_16x16x32_bf16 v[48:51], v[192:195], v[48:51], 0
	s_waitcnt lgkmcnt(2)
	v_mfma_f32_16x16x32_bf16 v[48:51], v[196:199], v[52:55], v[48:51]
	v_mfma_f32_16x16x32_bf16 v[138:141], v[142:145], v[52:55], v[138:141]
	s_waitcnt lgkmcnt(1)
	v_mfma_f32_16x16x32_bf16 v[48:51], v[208:211], v[56:59], v[48:51]
	v_mfma_f32_16x16x32_bf16 v[138:141], v[146:149], v[56:59], v[138:141]
	s_waitcnt lgkmcnt(0)
	v_mfma_f32_16x16x32_bf16 v[48:51], v[212:215], v[60:63], v[48:51]
	v_mfma_f32_16x16x32_bf16 v[138:141], v[150:153], v[60:63], v[138:141]
	s_barrier
	s_cmp_lg_u32 s42, 0
	s_cselect_b64 s[60:61], -1, 0
	s_or_b64 s[42:43], s[60:61], s[74:75]
	v_fmamk_f32 v52, v64, 0x3e0293ee, v89
	s_and_b64 vcc, s[42:43], s[6:7]
	v_cndmask_b32_e32 v52, v82, v52, vcc
	v_fmamk_f32 v53, v65, 0x3e0293ee, v90
	s_and_b64 vcc, s[42:43], s[8:9]
	v_cndmask_b32_e32 v53, v82, v53, vcc
	v_fmamk_f32 v55, v66, 0x3e0293ee, v91
	s_and_b64 vcc, s[42:43], s[10:11]
	v_cndmask_b32_e32 v55, v82, v55, vcc
	v_fmamk_f32 v56, v67, 0x3e0293ee, v92
	s_and_b64 vcc, s[42:43], s[12:13]
	v_cndmask_b32_e32 v56, v82, v56, vcc
	v_fmamk_f32 v57, v68, 0x3e0293ee, v93
	s_and_b64 vcc, s[42:43], s[14:15]
	v_cndmask_b32_e32 v57, v82, v57, vcc
	v_fmamk_f32 v58, v69, 0x3e0293ee, v94
	s_and_b64 vcc, s[42:43], s[16:17]
	v_cndmask_b32_e32 v58, v82, v58, vcc
	v_fmamk_f32 v59, v70, 0x3e0293ee, v95
	s_and_b64 vcc, s[42:43], s[18:19]
	v_cndmask_b32_e32 v59, v82, v59, vcc
	v_fmamk_f32 v60, v71, 0x3e0293ee, v96
	s_and_b64 vcc, s[42:43], s[20:21]
	v_cndmask_b32_e32 v60, v82, v60, vcc
	v_fmamk_f32 v61, v154, 0x3e0293ee, v97
	s_or_b64 vcc, s[60:61], s[76:77]
	v_fmamk_f32 v62, v155, 0x3e0293ee, v98
	v_fmamk_f32 v63, v156, 0x3e0293ee, v99
	v_fmamk_f32 v64, v157, 0x3e0293ee, v100
	v_fmamk_f32 v65, v158, 0x3e0293ee, v101
	v_fmamk_f32 v66, v159, 0x3e0293ee, v102
	v_fmamk_f32 v67, v160, 0x3e0293ee, v103
	v_fmamk_f32 v68, v161, 0x3e0293ee, v104
	v_cndmask_b32_e32 v61, v82, v61, vcc
	v_cndmask_b32_e32 v62, v82, v62, vcc
	v_cndmask_b32_e32 v63, v82, v63, vcc
	v_cndmask_b32_e32 v64, v82, v64, vcc
	v_cndmask_b32_e32 v65, v82, v65, vcc
	v_cndmask_b32_e32 v66, v82, v66, vcc
	v_cndmask_b32_e32 v67, v82, v67, vcc
	v_cndmask_b32_e32 v68, v82, v68, vcc
	v_fmamk_f32 v69, v130, 0x3e0293ee, v105
	s_or_b64 vcc, s[60:61], s[78:79]
	v_fmamk_f32 v130, v133, 0x3e0293ee, v108
	v_fmamk_f32 v70, v131, 0x3e0293ee, v106
	v_cndmask_b32_e32 v131, v82, v130, vcc
	v_fmamk_f32 v130, v134, 0x3e0293ee, v109
	s_mov_b32 s33, 0xff800000
	v_fmamk_f32 v71, v132, 0x3e0293ee, v107
	v_cndmask_b32_e32 v132, v82, v130, vcc
	v_fmamk_f32 v130, v135, 0x3e0293ee, v110
	v_max3_f32 v54, v52, s33, v53
	v_cndmask_b32_e32 v133, v82, v130, vcc
	v_fmamk_f32 v130, v136, 0x3e0293ee, v111
	v_max3_f32 v54, v54, v55, v56
	v_cndmask_b32_e32 v134, v82, v130, vcc
	v_fmamk_f32 v130, v137, 0x3e0293ee, v112
	v_max3_f32 v54, v54, v57, v58
	v_cndmask_b32_e32 v69, v82, v69, vcc
	v_cndmask_b32_e32 v70, v82, v70, vcc
	v_cndmask_b32_e32 v71, v82, v71, vcc
	v_cndmask_b32_e32 v135, v82, v130, vcc
	v_fmamk_f32 v130, v162, 0x3e0293ee, v113
	s_or_b64 vcc, s[60:61], s[80:81]
	v_max3_f32 v54, v54, v59, v60
	v_cndmask_b32_e32 v136, v82, v130, vcc
	v_fmamk_f32 v130, v163, 0x3e0293ee, v114
	v_max3_f32 v54, v54, v61, v62
	v_cndmask_b32_e32 v137, v82, v130, vcc
	v_fmamk_f32 v130, v164, 0x3e0293ee, v115
	v_max3_f32 v54, v54, v63, v64
	v_cndmask_b32_e32 v142, v82, v130, vcc
	v_fmamk_f32 v130, v165, 0x3e0293ee, v116
	v_max3_f32 v54, v54, v65, v66
	v_cndmask_b32_e32 v143, v82, v130, vcc
	v_fmamk_f32 v130, v166, 0x3e0293ee, v117
	v_max3_f32 v54, v54, v67, v68
	v_cndmask_b32_e32 v144, v82, v130, vcc
	v_fmamk_f32 v130, v167, 0x3e0293ee, v118
	v_max3_f32 v54, v54, v69, v70
	v_cndmask_b32_e32 v145, v82, v130, vcc
	v_fmamk_f32 v130, v168, 0x3e0293ee, v119
	v_max3_f32 v54, v54, v71, v131
	v_cndmask_b32_e32 v146, v82, v130, vcc
	v_fmamk_f32 v130, v169, 0x3e0293ee, v120
	s_or_b64 s[42:43], s[60:61], s[82:83]
	v_max3_f32 v54, v54, v132, v133
	v_cndmask_b32_e32 v147, v82, v130, vcc
	v_fmamk_f32 v130, v138, 0x3e0293ee, v121
	s_and_b64 vcc, s[42:43], s[22:23]
	v_max3_f32 v54, v54, v134, v135
	v_cndmask_b32_e32 v138, v82, v130, vcc
	v_fmamk_f32 v130, v139, 0x3e0293ee, v122
	s_and_b64 vcc, s[42:43], s[24:25]
	v_max3_f32 v54, v54, v136, v137
	v_cndmask_b32_e32 v139, v82, v130, vcc
	v_fmamk_f32 v130, v140, 0x3e0293ee, v123
	s_and_b64 vcc, s[42:43], s[26:27]
	v_max3_f32 v54, v54, v142, v143
	v_cndmask_b32_e32 v140, v82, v130, vcc
	v_fmamk_f32 v130, v141, 0x3e0293ee, v124
	s_and_b64 vcc, s[42:43], s[28:29]
	v_max3_f32 v54, v54, v144, v145
	v_cndmask_b32_e32 v141, v82, v130, vcc
	v_fmamk_f32 v48, v48, 0x3e0293ee, v125
	s_and_b64 vcc, s[42:43], s[30:31]
	v_max3_f32 v54, v54, v146, v147
	v_cndmask_b32_e32 v48, v82, v48, vcc
	v_fmamk_f32 v49, v49, 0x3e0293ee, v126
	s_and_b64 vcc, s[42:43], s[34:35]
	v_max3_f32 v54, v54, v138, v139
	v_cndmask_b32_e32 v49, v82, v49, vcc
	v_fmamk_f32 v50, v50, 0x3e0293ee, v127
	s_and_b64 vcc, s[42:43], s[36:37]
	v_max3_f32 v54, v54, v140, v141
	v_cndmask_b32_e32 v50, v82, v50, vcc
	v_fmamk_f32 v51, v51, 0x3e0293ee, v85
	s_and_b64 vcc, s[42:43], s[38:39]
	v_max3_f32 v54, v54, v48, v49
	v_cndmask_b32_e32 v51, v82, v51, vcc
	v_max3_f32 v54, v54, v50, v51
	v_mov_b32_e32 v130, v54
	s_nop 1
	v_permlane16_swap_b32 v54, v130
	s_waitcnt lgkmcnt(0)
	v_max_f32_e32 v130, v130, v130
	v_max_f32_e32 v54, v54, v130
	v_mov_b32_e32 v130, v54
	s_nop 1
	v_permlane32_swap_b32 v54, v130
	s_waitcnt lgkmcnt(0)
	v_max_f32_e32 v130, v130, v130
	v_max_f32_e32 v130, v54, v130
	v_sub_f32_e32 v52, v52, v130
	v_exp_f32_e32 v52, v52
	v_sub_f32_e32 v53, v53, v130
	v_exp_f32_e32 v53, v53
	v_sub_f32_e32 v54, v55, v130
	v_exp_f32_e32 v54, v54
	v_sub_f32_e32 v55, v56, v130
	v_exp_f32_e32 v55, v55
	v_sub_f32_e32 v57, v57, v130
	v_add_f32_e32 v56, 0, v52
	v_exp_f32_e32 v57, v57
	v_sub_f32_e32 v58, v58, v130
	v_add_f32_e32 v56, v53, v56
	v_exp_f32_e32 v58, v58
	v_sub_f32_e32 v59, v59, v130
	v_add_f32_e32 v56, v54, v56
	v_exp_f32_e32 v59, v59
	v_sub_f32_e32 v60, v60, v130
	v_add_f32_e32 v56, v55, v56
	v_exp_f32_e32 v60, v60
	v_sub_f32_e32 v61, v61, v130
	v_add_f32_e32 v56, v57, v56
	v_exp_f32_e32 v181, v61
	v_sub_f32_e32 v61, v62, v130
	v_add_f32_e32 v56, v58, v56
	v_exp_f32_e32 v183, v61
	v_sub_f32_e32 v61, v63, v130
	v_add_f32_e32 v56, v59, v56
	v_exp_f32_e32 v188, v61
	v_sub_f32_e32 v61, v64, v130
	v_add_f32_e32 v56, v60, v56
	v_exp_f32_e32 v189, v61
	v_sub_f32_e32 v61, v65, v130
	v_add_f32_e32 v56, v181, v56
	v_exp_f32_e32 v190, v61
	v_sub_f32_e32 v61, v66, v130
	v_add_f32_e32 v56, v183, v56
	v_exp_f32_e32 v191, v61
	v_sub_f32_e32 v61, v67, v130
	v_add_f32_e32 v56, v188, v56
	v_exp_f32_e32 v192, v61
	v_sub_f32_e32 v61, v68, v130
	v_add_f32_e32 v56, v189, v56
	v_exp_f32_e32 v193, v61
	v_sub_f32_e32 v61, v69, v130
	v_add_f32_e32 v56, v190, v56
	v_exp_f32_e32 v196, v61
	v_sub_f32_e32 v61, v70, v130
	v_add_f32_e32 v56, v191, v56
	v_exp_f32_e32 v197, v61
	v_sub_f32_e32 v61, v71, v130
	v_add_f32_e32 v56, v192, v56
	v_exp_f32_e32 v198, v61
	v_sub_f32_e32 v61, v131, v130
	v_add_f32_e32 v56, v193, v56
	v_exp_f32_e32 v199, v61
	v_sub_f32_e32 v61, v132, v130
	v_add_f32_e32 v56, v196, v56
	v_exp_f32_e32 v200, v61
	v_sub_f32_e32 v61, v133, v130
	v_add_f32_e32 v56, v197, v56
	v_exp_f32_e32 v201, v61
	v_sub_f32_e32 v61, v134, v130
	v_add_f32_e32 v56, v198, v56
	v_exp_f32_e32 v202, v61
	v_sub_f32_e32 v61, v135, v130
	v_add_f32_e32 v56, v199, v56
	v_exp_f32_e32 v203, v61
	v_sub_f32_e32 v61, v136, v130
	v_add_f32_e32 v56, v200, v56
	v_exp_f32_e32 v204, v61
	v_sub_f32_e32 v61, v137, v130
	v_add_f32_e32 v56, v201, v56
	v_exp_f32_e32 v205, v61
	v_sub_f32_e32 v61, v142, v130
	v_add_f32_e32 v56, v202, v56
	v_exp_f32_e32 v206, v61
	v_sub_f32_e32 v61, v143, v130
	v_add_f32_e32 v56, v203, v56
	v_exp_f32_e32 v207, v61
	v_sub_f32_e32 v61, v144, v130
	v_add_f32_e32 v56, v204, v56
	v_exp_f32_e32 v208, v61
	v_sub_f32_e32 v61, v145, v130
	v_add_f32_e32 v56, v205, v56
	v_exp_f32_e32 v209, v61
	v_sub_f32_e32 v61, v146, v130
	v_add_f32_e32 v56, v206, v56
	v_exp_f32_e32 v210, v61
	v_sub_f32_e32 v61, v147, v130
	v_add_f32_e32 v56, v207, v56
	v_exp_f32_e32 v211, v61
	v_sub_f32_e32 v61, v138, v130
	v_add_f32_e32 v56, v208, v56
	v_exp_f32_e32 v132, v61
	v_sub_f32_e32 v61, v139, v130
	v_add_f32_e32 v56, v209, v56
	v_exp_f32_e32 v133, v61
	v_sub_f32_e32 v61, v140, v130
	v_add_f32_e32 v56, v210, v56
	v_exp_f32_e32 v134, v61
	v_sub_f32_e32 v61, v141, v130
	v_add_f32_e32 v56, v211, v56
	v_exp_f32_e32 v135, v61
	v_sub_f32_e32 v48, v48, v130
	v_add_f32_e32 v56, v132, v56
	v_exp_f32_e32 v136, v48
	v_sub_f32_e32 v48, v49, v130
	v_add_f32_e32 v56, v133, v56
	v_exp_f32_e32 v137, v48
	v_sub_f32_e32 v48, v50, v130
	v_add_f32_e32 v56, v134, v56
	v_exp_f32_e32 v138, v48
	v_sub_f32_e32 v48, v51, v130
	v_add_f32_e32 v56, v135, v56
	v_exp_f32_e32 v139, v48
	v_add_f32_e32 v48, v136, v56
	v_add_f32_e32 v48, v137, v48
	v_add_f32_e32 v48, v138, v48
	v_add_f32_e32 v48, v139, v48
	v_mov_b32_e32 v49, v48
	s_nop 1
	v_permlane16_swap_b32 v48, v49
	v_cvt_pk_bf16_f32 v172, v52, v53
	v_cvt_pk_bf16_f32 v173, v54, v55
	v_cvt_pk_bf16_f32 v174, v57, v58
	v_cvt_pk_bf16_f32 v175, v59, v60
	s_waitcnt lgkmcnt(0)
	v_add_f32_e32 v48, v48, v49
	v_mov_b32_e32 v49, v48
	s_nop 1
	v_permlane32_swap_b32 v48, v49
	s_waitcnt lgkmcnt(0)
	v_add_f32_e32 v131, v48, v49
	s_cmp_eq_u32 s99, 1
	s_cbranch_scc1 .Lstg_p2_b
	s_barrier
.Lstg_p2_b:
	v_add_u32_e32 v48, s63, v88
	ds_read_b64_tr_b16 v[140:141], v48 offset:0
	ds_read_b64_tr_b16 v[142:143], v48 offset:0x440
	ds_read_b64_tr_b16 v[144:145], v48 offset:32
	ds_read_b64_tr_b16 v[146:147], v48 offset:0x460
	ds_read_b64_tr_b16 v[148:149], v48 offset:64
	ds_read_b64_tr_b16 v[150:151], v48 offset:0x480
	ds_read_b64_tr_b16 v[152:153], v48 offset:0x60
	ds_read_b64_tr_b16 v[154:155], v48 offset:0x4a0
	ds_read_b64_tr_b16 v[156:157], v48 offset:0x80
	ds_read_b64_tr_b16 v[158:159], v48 offset:0x4c0
	ds_read_b64_tr_b16 v[160:161], v48 offset:0xa0
	ds_read_b64_tr_b16 v[162:163], v48 offset:0x4e0
	ds_read_b64_tr_b16 v[164:165], v48 offset:0xc0
	ds_read_b64_tr_b16 v[166:167], v48 offset:0x500
	ds_read_b64_tr_b16 v[168:169], v48 offset:0xe0
	ds_read_b64_tr_b16 v[170:171], v48 offset:0x520
	s_waitcnt lgkmcnt(0)
	v_add_u32_e32 v194, s62, v88
	ds_read_b64_tr_b16 v[176:177], v194 offset:0
	ds_read_b64_tr_b16 v[178:179], v194 offset:0x440
	ds_read_b64_tr_b16 v[184:185], v194 offset:32
	ds_read_b64_tr_b16 v[186:187], v194 offset:0x460
	ds_read_b64_tr_b16 v[68:69], v194 offset:64
	ds_read_b64_tr_b16 v[70:71], v194 offset:0x480
	ds_read_b64_tr_b16 v[64:65], v194 offset:0x60
	ds_read_b64_tr_b16 v[66:67], v194 offset:0x4a0
	ds_read_b64_tr_b16 v[60:61], v194 offset:0x80
	ds_read_b64_tr_b16 v[62:63], v194 offset:0x4c0
	ds_read_b64_tr_b16 v[56:57], v194 offset:0xa0
	ds_read_b64_tr_b16 v[58:59], v194 offset:0x4e0
	ds_read_b64_tr_b16 v[52:53], v194 offset:0xc0
	ds_read_b64_tr_b16 v[54:55], v194 offset:0x500
	ds_read_b64_tr_b16 v[48:49], v194 offset:0xe0
	ds_read_b64_tr_b16 v[50:51], v194 offset:0x520
	s_waitcnt lgkmcnt(0)
	v_mfma_f32_16x16x32_bf16 v[140:143], v[140:143], v[172:175], 0
	v_mfma_f32_16x16x32_bf16 v[144:147], v[144:147], v[172:175], 0
	v_mfma_f32_16x16x32_bf16 v[148:151], v[148:151], v[172:175], 0
	v_mfma_f32_16x16x32_bf16 v[152:155], v[152:155], v[172:175], 0
	v_mfma_f32_16x16x32_bf16 v[156:159], v[156:159], v[172:175], 0
	v_mfma_f32_16x16x32_bf16 v[160:163], v[160:163], v[172:175], 0
	v_mfma_f32_16x16x32_bf16 v[164:167], v[164:167], v[172:175], 0
	v_mfma_f32_16x16x32_bf16 v[168:171], v[168:171], v[172:175], 0
	v_cvt_pk_bf16_f32 v172, v181, v183
	v_cvt_pk_bf16_f32 v173, v188, v189
	v_cvt_pk_bf16_f32 v174, v190, v191
	v_cvt_pk_bf16_f32 v175, v192, v193
	s_nop 1
	v_mfma_f32_16x16x32_bf16 v[140:143], v[176:179], v[172:175], v[140:143]
	v_add_u32_e32 v181, s95, v88
	ds_read_b64_tr_b16 v[176:177], v181 offset:0
	ds_read_b64_tr_b16 v[178:179], v181 offset:0x440
	v_mfma_f32_16x16x32_bf16 v[144:147], v[184:187], v[172:175], v[144:147]
	ds_read_b64_tr_b16 v[184:185], v181 offset:32
	ds_read_b64_tr_b16 v[186:187], v181 offset:0x460
	ds_read_b64_tr_b16 v[188:189], v181 offset:64
	ds_read_b64_tr_b16 v[190:191], v181 offset:0x480
	v_mfma_f32_16x16x32_bf16 v[68:71], v[68:71], v[172:175], v[148:151]
	ds_read_b64_tr_b16 v[148:149], v181 offset:0x60
	ds_read_b64_tr_b16 v[150:151], v181 offset:0x4a0
	v_cvt_pk_bf16_f32 v196, v196, v197
	v_mfma_f32_16x16x32_bf16 v[64:67], v[64:67], v[172:175], v[152:155]
	ds_read_b64_tr_b16 v[152:153], v181 offset:0x80
	ds_read_b64_tr_b16 v[154:155], v181 offset:0x4c0
	ds_read_b64_tr_b16 v[192:193], v181 offset:0xa0
	ds_read_b64_tr_b16 v[194:195], v181 offset:0x4e0
	v_mfma_f32_16x16x32_bf16 v[60:63], v[60:63], v[172:175], v[156:159]
	ds_read_b64_tr_b16 v[156:157], v181 offset:0xc0
	ds_read_b64_tr_b16 v[158:159], v181 offset:0x500
	v_cvt_pk_bf16_f32 v197, v198, v199
	v_mfma_f32_16x16x32_bf16 v[56:59], v[56:59], v[172:175], v[160:163]
	ds_read_b64_tr_b16 v[160:161], v181 offset:0xe0
	ds_read_b64_tr_b16 v[162:163], v181 offset:0x520
	s_waitcnt lgkmcnt(0)
	v_mfma_f32_16x16x32_bf16 v[48:51], v[48:51], v[172:175], v[168:171]
	v_cvt_pk_bf16_f32 v198, v200, v201
	v_cvt_pk_bf16_f32 v199, v202, v203
	v_mfma_f32_16x16x32_bf16 v[52:55], v[52:55], v[172:175], v[164:167]
	v_add_u32_e32 v181, s41, v88
	ds_read_b64_tr_b16 v[164:165], v181 offset:0
	ds_read_b64_tr_b16 v[166:167], v181 offset:0x440
	ds_read_b64_tr_b16 v[168:169], v181 offset:32
	ds_read_b64_tr_b16 v[170:171], v181 offset:0x460
	ds_read_b64_tr_b16 v[172:173], v181 offset:64
	ds_read_b64_tr_b16 v[174:175], v181 offset:0x480
	v_mfma_f32_16x16x32_bf16 v[140:143], v[176:179], v[196:199], v[140:143]
	ds_read_b64_tr_b16 v[176:177], v181 offset:0x60
	ds_read_b64_tr_b16 v[178:179], v181 offset:0x4a0
	v_mfma_f32_16x16x32_bf16 v[64:67], v[148:151], v[196:199], v[64:67]
	ds_read_b64_tr_b16 v[148:149], v181 offset:0x80
	ds_read_b64_tr_b16 v[150:151], v181 offset:0x4c0
	v_mfma_f32_16x16x32_bf16 v[144:147], v[184:187], v[196:199], v[144:147]
	ds_read_b64_tr_b16 v[184:185], v181 offset:0xa0
	ds_read_b64_tr_b16 v[186:187], v181 offset:0x4e0
	v_mfma_f32_16x16x32_bf16 v[60:63], v[152:155], v[196:199], v[60:63]
	ds_read_b64_tr_b16 v[152:153], v181 offset:0xc0
	ds_read_b64_tr_b16 v[154:155], v181 offset:0x500
	v_mfma_f32_16x16x32_bf16 v[68:71], v[188:191], v[196:199], v[68:71]
	ds_read_b64_tr_b16 v[188:189], v181 offset:0xe0
	ds_read_b64_tr_b16 v[190:191], v181 offset:0x520
	s_waitcnt lgkmcnt(0)
	v_mfma_f32_16x16x32_bf16 v[48:51], v[160:163], v[196:199], v[48:51]
	v_mfma_f32_16x16x32_bf16 v[56:59], v[192:195], v[196:199], v[56:59]
	v_cvt_pk_bf16_f32 v192, v204, v205
	v_cvt_pk_bf16_f32 v193, v206, v207
	v_cvt_pk_bf16_f32 v194, v208, v209
	v_mfma_f32_16x16x32_bf16 v[52:55], v[156:159], v[196:199], v[52:55]
	v_cvt_pk_bf16_f32 v195, v210, v211
	v_add_u32_e32 v181, s40, v88
	ds_read_b64_tr_b16 v[156:157], v181 offset:0
	ds_read_b64_tr_b16 v[158:159], v181 offset:0x440
	ds_read_b64_tr_b16 v[160:161], v181 offset:32
	ds_read_b64_tr_b16 v[162:163], v181 offset:0x460
	s_nop 0
	v_mfma_f32_16x16x32_bf16 v[140:143], v[164:167], v[192:195], v[140:143]
	ds_read_b64_tr_b16 v[164:165], v181 offset:64
	ds_read_b64_tr_b16 v[166:167], v181 offset:0x480
	v_mfma_f32_16x16x32_bf16 v[144:147], v[168:171], v[192:195], v[144:147]
	ds_read_b64_tr_b16 v[168:169], v181 offset:0x60
	ds_read_b64_tr_b16 v[170:171], v181 offset:0x4a0
	v_mfma_f32_16x16x32_bf16 v[60:63], v[148:151], v[192:195], v[60:63]
	ds_read_b64_tr_b16 v[148:149], v181 offset:0x80
	ds_read_b64_tr_b16 v[150:151], v181 offset:0x4c0
	v_mfma_f32_16x16x32_bf16 v[68:71], v[172:175], v[192:195], v[68:71]
	ds_read_b64_tr_b16 v[172:173], v181 offset:0xa0
	ds_read_b64_tr_b16 v[174:175], v181 offset:0x4e0
	v_mfma_f32_16x16x32_bf16 v[64:67], v[176:179], v[192:195], v[64:67]
	ds_read_b64_tr_b16 v[176:177], v181 offset:0xc0
	ds_read_b64_tr_b16 v[178:179], v181 offset:0x500
	v_mfma_f32_16x16x32_bf16 v[52:55], v[152:155], v[192:195], v[52:55]
	ds_read_b64_tr_b16 v[152:153], v181 offset:0xe0
	ds_read_b64_tr_b16 v[154:155], v181 offset:0x520
	s_waitcnt lgkmcnt(0)
	v_mfma_f32_16x16x32_bf16 v[56:59], v[184:187], v[192:195], v[56:59]
	v_mfma_f32_16x16x32_bf16 v[184:187], v[188:191], v[192:195], v[48:51]
	v_cvt_pk_bf16_f32 v132, v132, v133
	v_cvt_pk_bf16_f32 v133, v134, v135
	v_cvt_pk_bf16_f32 v134, v136, v137
	v_cvt_pk_bf16_f32 v135, v138, v139
	v_add_u32_e32 v48, s96, v129
	v_ashrrev_i32_e32 v49, 31, v48
	v_mfma_f32_16x16x32_bf16 v[136:139], v[156:159], v[132:135], v[140:143]
	v_rcp_f32_e32 v156, v131
	v_lshl_add_u64 v[48:49], s[44:45], 0, v[48:49]
	v_lshlrev_b64 v[50:51], 11, v[48:49]
	v_mfma_f32_16x16x32_bf16 v[140:143], v[160:163], v[132:135], v[144:147]
	v_mfma_f32_16x16x32_bf16 v[68:71], v[164:167], v[132:135], v[68:71]
	s_nop 1
	v_lshl_add_u64 v[144:145], v[78:79], 0, v[50:51]
	v_pk_mul_f32 v[50:51], v[156:157], v[136:137] op_sel_hi:[0,1]
	v_pk_mul_f32 v[136:137], v[156:157], v[138:139] op_sel_hi:[0,1]
	v_cvt_pk_bf16_f32 v50, v50, v51
	v_cvt_pk_bf16_f32 v51, v136, v137
	v_mfma_f32_16x16x32_bf16 v[64:67], v[168:171], v[132:135], v[64:67]
	global_store_dwordx2 v[144:145], v[50:51], off
	v_pk_mul_f32 v[50:51], v[156:157], v[140:141] op_sel_hi:[0,1]
	v_pk_mul_f32 v[136:137], v[156:157], v[142:143] op_sel_hi:[0,1]
	v_cvt_pk_bf16_f32 v50, v50, v51
	v_cvt_pk_bf16_f32 v51, v136, v137
	v_mfma_f32_16x16x32_bf16 v[60:63], v[148:151], v[132:135], v[60:63]
	global_store_dwordx2 v[144:145], v[50:51], off offset:32
	v_pk_mul_f32 v[136:137], v[156:157], v[70:71] op_sel_hi:[0,1]
	v_mfma_f32_16x16x32_bf16 v[50:53], v[176:179], v[132:135], v[52:55]
	s_nop 2
	v_mul_f32_e64 v54, v156, v68
	v_mul_f32_e64 v55, v156, v69
	v_cvt_pk_bf16_f32 v54, v54, v55
	v_cvt_pk_bf16_f32 v55, v136, v137
	v_mfma_f32_16x16x32_bf16 v[56:59], v[172:175], v[132:135], v[56:59]
	global_store_dwordx2 v[144:145], v[54:55], off offset:64
	v_pk_mul_f32 v[54:55], v[156:157], v[64:65] op_sel_hi:[0,1]
	v_pk_mul_f32 v[64:65], v[156:157], v[66:67] op_sel_hi:[0,1]
	v_mfma_f32_16x16x32_bf16 v[68:71], v[152:155], v[132:135], v[184:187]
	v_cvt_pk_bf16_f32 v54, v54, v55
	v_cvt_pk_bf16_f32 v55, v64, v65
	global_store_dwordx2 v[144:145], v[54:55], off offset:96
	v_pk_mul_f32 v[54:55], v[156:157], v[60:61] op_sel_hi:[0,1]
	v_pk_mul_f32 v[60:61], v[156:157], v[62:63] op_sel_hi:[0,1]
	v_pk_mul_f32 v[50:51], v[156:157], v[50:51] op_sel_hi:[0,1]
	v_pk_mul_f32 v[52:53], v[156:157], v[52:53] op_sel_hi:[0,1]
	v_cvt_pk_bf16_f32 v54, v54, v55
	v_cvt_pk_bf16_f32 v55, v60, v61
	v_cvt_pk_bf16_f32 v50, v50, v51
	v_cvt_pk_bf16_f32 v51, v52, v53
	global_store_dwordx2 v[144:145], v[54:55], off offset:128
	v_pk_mul_f32 v[54:55], v[156:157], v[56:57] op_sel_hi:[0,1]
	v_pk_mul_f32 v[56:57], v[156:157], v[58:59] op_sel_hi:[0,1]
	global_store_dwordx2 v[144:145], v[50:51], off offset:192
	v_pk_mul_f32 v[50:51], v[156:157], v[68:69] op_sel_hi:[0,1]
	v_pk_mul_f32 v[52:53], v[156:157], v[70:71] op_sel_hi:[0,1]
	v_cvt_pk_bf16_f32 v54, v54, v55
	v_cvt_pk_bf16_f32 v55, v56, v57
	v_cvt_pk_bf16_f32 v50, v50, v51
	v_cvt_pk_bf16_f32 v51, v52, v53
	global_store_dwordx2 v[144:145], v[54:55], off offset:160
	global_store_dwordx2 v[144:145], v[50:51], off offset:224
	s_and_saveexec_b64 s[40:41], s[4:5]
	s_cbranch_execz .LBB0_416
	v_log_f32_e32 v50, v131
	v_lshlrev_b64 v[48:49], 5, v[48:49]
	v_lshl_add_u64 v[48:49], s[84:85], 0, v[48:49]
	v_add_f32_e32 v50, v130, v50
	v_mul_f32_e32 v50, 0x3f317218, v50
	global_store_dword v[48:49], v50, off

.LBB0_677:
	s_or_b64 exec, exec, s[0:1]
	v_add_u32_e32 v46, 0xc0, v152
	s_waitcnt lgkmcnt(1)
	ds_read2st64_b32 v[44:45], v46 offset0:2 offset1:6
	s_waitcnt lgkmcnt(1)
	ds_read2st64_b32 v[46:47], v46 offset0:10 offset1:14
	ds_read_b32 v48, v174 offset:704
	ds_read_b32 v49, v175 offset:704
	ds_read_b32 v50, v176 offset:704
	s_waitcnt lgkmcnt(4)
	v_add_f32_e32 v44, v44, v45
	s_waitcnt lgkmcnt(3)
	v_add_f32_e32 v44, v44, v46
	v_add_f32_e32 v44, v44, v47
	s_waitcnt lgkmcnt(1)
	v_fmac_f32_e32 v44, v48, v49
	s_waitcnt lgkmcnt(0)
	v_max_f32_e32 v45, v50, v50
	v_max_f32_e64 v44, |v44|, v45
	v_rcp_f32_e32 v44, v44
	v_and_b32_e32 v50, 0xffff0000, v86
	v_mul_f32_e32 v50, 0xbfb8aa3b, v50
	v_exp_f32_e32 v51, v50
	v_pk_mul_f32 v[42:43], v[42:43], v[44:45] op_sel_hi:[1,0]
	v_pk_mul_f32 v[40:41], v[40:41], v[44:45] op_sel_hi:[1,0]
	v_pk_mul_f32 v[46:47], v[2:3], v[44:45] op_sel_hi:[1,0]
	v_pk_mul_f32 v[48:49], v[0:1], v[44:45] op_sel_hi:[1,0]
	v_lshlrev_b32_e32 v45, 16, v86
	v_mul_f32_e32 v45, 0xbfb8aa3b, v45
	v_exp_f32_e32 v45, v45
	v_lshlrev_b32_e32 v2, 16, v84
	v_and_b32_e32 v3, 0xffff0000, v84
	v_mul_f32_e32 v2, 0xbfb8aa3b, v2
	v_add_f32_e32 v45, 1.0, v45
	v_rcp_f32_e32 v50, v45
	v_add_f32_e32 v45, 1.0, v51
	v_lshlrev_b32_e32 v51, 16, v87
	v_mul_f32_e32 v51, 0xbfb8aa3b, v51
	v_exp_f32_e32 v52, v51
	v_and_b32_e32 v51, 0xffff0000, v87
	v_mul_f32_e32 v51, 0xbfb8aa3b, v51
	v_mul_f32_e32 v3, 0xbfb8aa3b, v3
	v_exp_f32_e32 v53, v51
	v_exp_f32_e32 v2, v2
	v_exp_f32_e32 v3, v3
	v_rcp_f32_e32 v51, v45
	v_add_f32_e32 v45, 1.0, v52
	v_rcp_f32_e32 v52, v45
	v_add_f32_e32 v45, 1.0, v53
	v_add_f32_e32 v0, 1.0, v2
	v_add_f32_e32 v1, 1.0, v3
	v_lshlrev_b32_e32 v2, 16, v85
	v_and_b32_e32 v3, 0xffff0000, v85
	v_rcp_f32_e32 v53, v45
	v_pk_mul_f32 v[84:85], v[50:51], v[48:49]
	v_pk_mul_f32 v[38:39], v[38:39], v[44:45] op_sel_hi:[1,0]
	v_pk_mul_f32 v[36:37], v[36:37], v[44:45] op_sel_hi:[1,0]
	v_pk_mul_f32 v[34:35], v[34:35], v[44:45] op_sel_hi:[1,0]
	v_lshlrev_b32_e32 v45, 16, v80
	v_and_b32_e32 v50, 0xffff0000, v80
	v_mul_f32_e32 v45, 0xbfb8aa3b, v45
	v_mul_f32_e32 v50, 0xbfb8aa3b, v50
	v_exp_f32_e32 v45, v45
	v_exp_f32_e32 v50, v50
	v_mul_f32_e32 v2, 0xbfb8aa3b, v2
	v_mul_f32_e32 v3, 0xbfb8aa3b, v3
	v_pk_mul_f32 v[76:77], v[52:53], v[46:47]
	v_pk_mul_f32 v[32:33], v[32:33], v[44:45] op_sel_hi:[1,0]
	v_add_f32_e32 v44, 1.0, v45
	v_add_f32_e32 v45, 1.0, v50
	v_lshlrev_b32_e32 v50, 16, v81
	v_and_b32_e32 v51, 0xffff0000, v81
	v_lshlrev_b32_e32 v52, 16, v82
	v_and_b32_e32 v53, 0xffff0000, v82
	v_exp_f32_e32 v2, v2
	v_exp_f32_e32 v3, v3
	v_mul_f32_e32 v50, 0xbfb8aa3b, v50
	v_mul_f32_e32 v51, 0xbfb8aa3b, v51
	v_mul_f32_e32 v52, 0xbfb8aa3b, v52
	v_mul_f32_e32 v53, 0xbfb8aa3b, v53
	v_exp_f32_e32 v50, v50
	v_exp_f32_e32 v51, v51
	v_exp_f32_e32 v52, v52
	v_exp_f32_e32 v53, v53
	v_lshlrev_b32_e32 v54, 16, v83
	v_and_b32_e32 v55, 0xffff0000, v83
	v_rcp_f32_e32 v0, v0
	v_rcp_f32_e32 v1, v1
	v_add_f32_e32 v2, 1.0, v2
	v_add_f32_e32 v3, 1.0, v3
	v_mul_f32_e32 v54, 0xbfb8aa3b, v54
	v_mul_f32_e32 v55, 0xbfb8aa3b, v55
	v_rcp_f32_e32 v2, v2
	v_rcp_f32_e32 v3, v3
	v_rcp_f32_e32 v44, v44
	v_rcp_f32_e32 v45, v45
	v_add_f32_e32 v50, 1.0, v50
	v_add_f32_e32 v51, 1.0, v51
	v_add_f32_e32 v52, 1.0, v52
	v_add_f32_e32 v53, 1.0, v53
	v_exp_f32_e32 v54, v54
	v_exp_f32_e32 v55, v55
	v_rcp_f32_e32 v50, v50
	v_rcp_f32_e32 v51, v51
	v_rcp_f32_e32 v52, v52
	v_rcp_f32_e32 v53, v53
	v_pk_mul_f32 v[0:1], v[0:1], v[40:41]
	v_pk_mul_f32 v[2:3], v[2:3], v[42:43]
	v_add_f32_e32 v40, v0, v1
	v_add_f32_e32 v54, 1.0, v54
	v_add_f32_e32 v55, 1.0, v55
	v_pk_mul_f32 v[82:83], v[44:45], v[36:37]
	v_add_f32_e32 v40, v2, v40
	v_rcp_f32_e32 v54, v54
	v_rcp_f32_e32 v55, v55
	v_pk_mul_f32 v[80:81], v[50:51], v[38:39]
	v_pk_mul_f32 v[74:75], v[52:53], v[32:33]
	v_add_f32_e32 v32, v82, v83
	v_add_f32_e32 v40, v3, v40
	v_add_f32_e32 v32, v80, v32
	v_add_f32_e32 v40, v84, v40
	v_add_f32_e32 v32, v81, v32
	v_add_f32_e32 v40, v85, v40
	v_add_f32_e32 v32, v74, v32
	v_add_f32_e32 v40, v76, v40
	v_pk_mul_f32 v[72:73], v[54:55], v[34:35]
	v_add_f32_e32 v32, v75, v32
	v_add_f32_e32 v40, v77, v40
	v_add_f32_e32 v32, v72, v32
	v_add_f32_e32 v56, 0, v40
	v_add_f32_e32 v32, v73, v32
	v_pk_mul_f32 v[40:41], v[0:1], v[0:1]
	v_add_f32_e32 v44, v32, v56
	v_pk_mul_f32 v[32:33], v[82:83], v[82:83]
	v_pk_mul_f32 v[42:43], v[2:3], v[2:3]
	v_pk_mul_f32 v[34:35], v[80:81], v[80:81]
	v_add_f32_e32 v32, v32, v33
	v_add_f32_e32 v33, v40, v41
	v_add_f32_e32 v32, v34, v32
	v_add_f32_e32 v33, v42, v33
	v_pk_mul_f32 v[46:47], v[84:85], v[84:85]
	v_pk_mul_f32 v[36:37], v[74:75], v[74:75]
	v_add_f32_e32 v32, v35, v32
	v_add_f32_e32 v33, v43, v33
	v_add_f32_e32 v32, v36, v32
	v_add_f32_e32 v33, v46, v33
	v_pk_mul_f32 v[48:49], v[76:77], v[76:77]
	v_pk_mul_f32 v[38:39], v[72:73], v[72:73]
	v_add_f32_e32 v32, v37, v32
	v_add_f32_e32 v33, v47, v33
	v_add_f32_e32 v32, v38, v32
	v_add_f32_e32 v33, v48, v33
	v_add_f32_e32 v32, v39, v32
	v_add_f32_e32 v33, v49, v33
	v_add_f32_e32 v35, v33, v32
	v_mov_b32_e32 v34, v44
	s_nop 1
	v_permlane16_swap_b32 v44, v34
	v_mov_b32_e32 v36, v35
	s_nop 1
	v_permlane16_swap_b32 v35, v36
	s_lshl_b64 s[0:1], s[20:21], 10
	s_waitcnt lgkmcnt(1)
	v_add_f32_e32 v32, v44, v34
	s_waitcnt lgkmcnt(0)
	v_add_f32_e32 v34, v35, v36
	v_mov_b32_e32 v33, v32
	s_nop 1
	v_permlane32_swap_b32 v32, v33
	v_mov_b32_e32 v35, v34
	s_nop 1
	v_permlane32_swap_b32 v34, v35
	s_and_saveexec_b64 s[20:21], vcc
	s_cbranch_execz .LBB0_614
	s_waitcnt lgkmcnt(1)
	v_add_f32_e32 v32, v32, v33
	s_waitcnt lgkmcnt(0)
	v_add_f32_e32 v33, v34, v35
	v_add_u32_e32 v34, 0xc0, v177
	ds_write2st64_b32 v34, v32, v33 offset0:2 offset1:18
	s_branch .LBB0_614
	s_nop 0
	s_nop 0
	s_nop 0
	s_nop 0
	s_nop 0
	s_nop 0
	s_nop 0
	s_nop 0
	s_nop 0
	s_nop 0
	s_nop 0
	s_nop 0
	s_nop 0
	s_nop 0
	s_nop 0
	s_nop 0
	s_nop 0
	s_nop 0
	s_nop 0
	s_nop 0
	s_nop 0
	s_nop 0
	s_nop 0
	s_nop 0
	s_nop 0
	s_nop 0
	s_nop 0
	s_nop 0
	s_nop 0
	s_nop 0
	s_nop 0
	s_nop 0
	s_nop 0
	s_nop 0
	s_nop 0
	s_nop 0
	s_nop 0
	s_nop 0
	s_nop 0
	s_nop 0
	s_nop 0
	s_nop 0
	s_nop 0
	s_nop 0
	s_nop 0
	s_nop 0
	s_nop 0
	s_nop 0
	s_nop 0
	s_nop 0
	s_nop 0
	s_nop 0
	s_nop 0
	s_nop 0
	s_nop 0
	s_nop 0
	s_nop 0
	s_nop 0
	s_nop 0
	s_nop 0
	s_nop 0
	s_nop 0
	s_nop 0
	s_nop 0
	s_nop 0
	s_nop 0
	s_nop 0
	s_nop 0
	s_nop 0
	s_nop 0
	s_nop 0
	s_nop 0
	s_nop 0
	s_nop 0
	s_nop 0
	s_nop 0
	s_nop 0
	s_nop 0
	s_nop 0
	s_nop 0
	s_nop 0
	s_nop 0
	s_nop 0
	s_nop 0
	s_nop 0
	s_nop 0
	s_nop 0
	s_nop 0
	s_nop 0
	s_nop 0
	s_nop 0
	s_nop 0
	s_nop 0
	s_nop 0
	s_nop 0
	s_nop 0
	s_nop 0
	s_nop 0
	s_nop 0
	s_nop 0
	s_nop 0
	s_nop 0
	s_nop 0
	s_nop 0
	s_nop 0
	s_nop 0
	s_nop 0
